# same as previous version (NA bias loads de-serialized, norm_prepass loads issued up front) plus unreachable padding so every hot loop head keeps the baseline's address modulo 256
# baseline (speedup 1.0000x reference)
;   DI bool next(int i, Unit& u) const {
;     if ((long)i * G + c >= nwg) return false;
;     const int ii = rev ? ((nwg - c + G - 1) / G - 1 - i) : i;
;     const long L = (long)ii * G + c;
;     int wgid = (int)L; { const int q = nwg / NXCD, r = nwg % NXCD, xcd = wgid % NXCD, off = wgid / NXCD; wgid = (xcd < r ? xcd * (q + 1) : r * (q + 1) + (xcd - r) * q) + off; }
;     const int nig = WGM * nN, gid = wgid / nig, fm = gid * WGM, gsz = (nM - fm) < WGM ? (nM - fm) : WGM;
;     u.pm = fm + ((wgid % nig) % gsz); u.pn = (wgid % nig) / gsz; if (revn) u.pn = nN - 1 - u.pn; return true;
;   }
.LBB0_331:
	v_readlane_b32 s83, v241, 0
	s_ashr_i32 s10, s83, 31
	s_lshr_b32 s0, s10, 29
	s_add_i32 s0, s83, s0
	s_and_b32 s1, s0, -8
	s_sub_i32 s54, s83, s1
	s_add_i32 s1, s26, s83
	s_ashr_i32 s2, s1, 31
	s_lshr_b32 s2, s2, 29
	s_add_i32 s2, s1, s2
	s_and_b32 s3, s2, -8
	s_sub_i32 s45, s1, s3
	s_add_i32 s1, s1, s26
	s_ashr_i32 s3, s1, 31
	s_lshr_b32 s3, s3, 29
	s_add_i32 s3, s1, s3
	s_and_b32 s4, s3, -8
	s_sub_i32 s44, s1, s4
	s_add_i32 s1, s1, s26
	s_ashr_i32 s4, s1, 31
	s_lshr_b32 s4, s4, 29
	s_add_i32 s22, s1, s4
	s_and_b32 s4, s22, -8
	s_sub_i32 s37, s1, s4
	s_add_i32 s1, s1, s26
	s_ashr_i32 s4, s1, 31
	s_lshr_b32 s4, s4, 29
	s_add_i32 s23, s1, s4
	s_and_b32 s4, s23, -8
	s_sub_i32 s35, s1, s4
	s_add_i32 s1, s1, s26
	s_ashr_i32 s4, s1, 31
	s_lshr_b32 s4, s4, 29
	s_add_i32 s28, s1, s4
	s_and_b32 s4, s28, -8
	s_sub_i32 s31, s1, s4
	s_add_i32 s1, s1, s26
	s_ashr_i32 s4, s1, 31
	s_lshr_b32 s4, s4, 29
	s_add_i32 s29, s1, s4
	s_and_b32 s4, s29, -8
	s_sub_i32 s19, s1, s4
	s_add_i32 s1, s1, s26
	s_ashr_i32 s4, s1, 31
	s_lshr_b32 s4, s4, 29
	s_add_i32 s30, s1, s4
	s_and_b32 s4, s30, -8
	s_sub_i32 s18, s1, s4
	s_lshl_b32 s1, s54, 8
	s_lshl_b32 s4, s45, 8
	s_lshl_b32 s8, s44, 8
	s_lshl_b32 s11, s37, 8
	s_lshl_b32 s9, s35, 8
	s_lshl_b32 s7, s31, 8
	s_lshl_b32 s6, s19, 8
	s_lshl_b32 s5, s18, 8
	s_cmp_lt_i32 s18, 0
	s_movk_i32 s16, 0xc1
	s_movk_i32 s17, 0x91
	s_mul_i32 s12, s18, 0x101
	s_cselect_b32 s33, s16, 0xc0
	s_cselect_b32 s34, s17, 0x90
	s_cselect_b32 s5, s12, s5
	s_cmp_lt_i32 s19, 0
	s_mul_i32 s12, s19, 0x101
	s_cselect_b32 s36, s16, 0xc0
	s_cselect_b32 s39, s17, 0x90
	s_cselect_b32 s6, s12, s6
	s_cmp_lt_i32 s31, 0
	s_mul_i32 s12, s31, 0x101
	s_cselect_b32 s38, s16, 0xc0
	s_cselect_b32 s47, s17, 0x90
	s_cselect_b32 s7, s12, s7
	s_cmp_lt_i32 s35, 0
	s_mul_i32 s12, s35, 0x101
	s_cselect_b32 s40, s16, 0xc0
	s_cselect_b32 s51, s17, 0x90
	s_cselect_b32 s9, s12, s9
	s_cmp_lt_i32 s37, 0
	s_mul_i32 s12, s37, 0x101
	s_cselect_b32 s41, s16, 0xc0
	s_cselect_b32 s56, s17, 0x90
	s_cselect_b32 s11, s12, s11
	s_cmp_lt_i32 s44, 0
	s_mul_i32 s12, s44, 0x101
	s_cselect_b32 s21, s16, 0xc0
	s_cselect_b32 s58, s17, 0x90
	s_cselect_b32 s13, s12, s8
	s_cmp_lt_i32 s45, 0
	s_mul_i32 s12, s45, 0x101
	s_cselect_b32 s8, s16, 0xc0
	s_cselect_b32 s62, s17, 0x90
	s_cselect_b32 s14, s12, s4
	s_cmp_lt_i32 s54, 0
	s_mul_i32 s4, s54, 0x101
	s_cselect_b32 s15, s4, s1
	s_lshl_b32 s1, s54, 6
	s_cmp_lt_i32 s54, 0
	s_mul_i32 s4, s54, 0x41
	s_cselect_b32 s12, s16, 0xc0
	s_cselect_b32 s63, s17, 0x90
	s_cselect_b32 s17, s4, s1
	s_not_b32 s1, s83
	s_lshr_b32 s89, s26, 3
	s_lshr_b32 s4, s83, 3
	s_add_i32 s92, s26, s1
	s_ashr_i32 s27, s26, 31
	s_sub_u32 s90, 0x600, s83
	s_subb_u32 s91, 0, s10
	s_cmpk_lt_i32 s83, 0x600
	s_cselect_b64 s[42:43], -1, 0
	s_mul_i32 s1, s12, s54
	s_ashr_i32 s16, s0, 3
	s_add_i32 s1, s1, s16
	s_mul_hi_i32 s0, s1, 0x2aaaaaab
	s_lshr_b32 s12, s0, 31
	s_ashr_i32 s0, s0, 4
	s_add_i32 s64, s0, s12
	s_mul_i32 s0, s64, 0x60
	s_sub_i32 s0, s1, s0
	s_bfe_i32 s1, s0, 0x80000
	s_bfe_u32 s1, s1, 0x3000c
	s_add_i32 s1, s0, s1
	s_bfe_i32 s12, s1, 0x80000
	s_and_b32 s1, s1, 0xf8
	s_sub_i32 s0, s0, s1
	s_sext_i32_i8 s67, s0
	v_writelane_b32 v241, s42, 47
	s_lshl_b32 s0, s64, 11
	s_lshl_b32 s1, s67, 8
	v_writelane_b32 v241, s43, 48
	s_add_i32 s0, s1, s0
	v_writelane_b32 v241, s0, 49
	s_mul_i32 s0, s8, s45
	s_ashr_i32 s20, s2, 3
	s_add_i32 s0, s0, s20
	s_mul_hi_i32 s1, s0, 0x2aaaaaab
	s_lshr_b32 s2, s1, 31
	s_ashr_i32 s1, s1, 4
	s_add_i32 s1, s1, s2
	s_mul_i32 s2, s1, 0x60
	s_sub_i32 s8, s0, s2
	s_mul_i32 s2, s21, s44
	s_ashr_i32 s21, s3, 3
	s_add_i32 s2, s2, s21
	s_mul_hi_i32 s3, s2, 0x2aaaaaab
	s_lshr_b32 s42, s3, 31
	s_ashr_i32 s3, s3, 4
	s_add_i32 s3, s3, s42
	s_mul_i32 s42, s3, 0x60
	s_mul_i32 s41, s41, s37
	s_lshl_b32 s55, s3, 3
	s_ashr_i32 s22, s22, 3
	s_sub_i32 s60, s2, s42
	s_sub_i32 s2, 0x80, s55
	s_add_i32 s41, s41, s22
	s_min_i32 s65, s2, 8
	s_mul_hi_i32 s2, s41, 0x2aaaaaab
	s_lshr_b32 s3, s2, 31
	s_ashr_i32 s2, s2, 4
	s_add_i32 s2, s2, s3
	s_mul_i32 s40, s40, s35
	s_ashr_i32 s23, s23, 3
	s_mul_i32 s3, s2, 0x60
	s_add_i32 s40, s40, s23
	s_sub_i32 s53, s41, s3
	s_mul_hi_i32 s41, s40, 0x2aaaaaab
	s_lshr_b32 s42, s41, 31
	s_ashr_i32 s41, s41, 4
	s_add_i32 s41, s41, s42
	s_mul_i32 s42, s41, 0x60
	s_mul_i32 s38, s38, s31
	s_lshl_b32 s46, s41, 3
	s_ashr_i32 s28, s28, 3
	s_sub_i32 s50, s40, s42
	s_sub_i32 s40, 0x80, s46
	s_add_i32 s38, s38, s28
	s_min_i32 s57, s40, 8
	s_mul_hi_i32 s40, s38, 0x2aaaaaab
	s_lshr_b32 s41, s40, 31
	s_ashr_i32 s40, s40, 4
	s_add_i32 s40, s40, s41
	s_mul_i32 s41, s40, 0x60
	s_mul_i32 s36, s36, s19
	s_lshl_b32 s42, s40, 3
	s_ashr_i32 s29, s29, 3
	s_sub_i32 s43, s38, s41
	s_sub_i32 s38, 0x80, s42
	s_add_i32 s36, s36, s29
	s_min_i32 s52, s38, 8
	s_mul_hi_i32 s38, s36, 0x2aaaaaab
	s_lshr_b32 s40, s38, 31
	s_ashr_i32 s38, s38, 4
	s_add_i32 s38, s38, s40
	s_mul_i32 s40, s38, 0x60
	s_mul_i32 s33, s33, s18
	s_lshl_b32 s38, s38, 3
	s_ashr_i32 s30, s30, 3
	s_sub_i32 s40, s36, s40
	s_sub_i32 s36, 0x80, s38
	s_add_i32 s33, s33, s30
	s_min_i32 s48, s36, 8
	s_mul_hi_i32 s36, s33, 0x2aaaaaab
	s_lshr_b32 s41, s36, 31
	s_ashr_i32 s36, s36, 4
	s_add_i32 s41, s36, s41
	s_mul_i32 s36, s41, 0x60
	s_lshl_b32 s64, s64, 3
	s_lshl_b32 s59, s1, 3
	s_lshl_b32 s49, s2, 3
	s_sub_i32 s36, s33, s36
	s_lshl_b32 s33, s41, 3
	s_add_i32 s64, s64, s67
	s_sext_i32_i16 s66, s12
	s_sub_i32 s0, 0x80, s59
	s_sub_i32 s2, 0x80, s49
	s_sub_i32 s41, 0x80, s33
	v_writelane_b32 v241, s64, 50
	s_min_i32 s12, s0, 8
	s_lshl_b64 s[0:1], s[26:27], 1
	s_min_i32 s61, s2, 8
	s_lshl_b64 s[2:3], s[26:27], 2
	s_min_i32 s41, s41, 8
	v_writelane_b32 v241, s65, 51
	s_ashr_i32 s64, s66, 3
; DI unsigned xb_ld(unsigned* p)              { return __hip_atomic_load(p, __ATOMIC_RELAXED, __HIP_MEMORY_SCOPE_AGENT); }
;   DI bool next(int i, Unit& u) const {
;     if ((long)i * G + c >= nwg) return false;
;     const int ii = rev ? ((nwg - c + G - 1) / G - 1 - i) : i;
;     const long L = (long)ii * G + c;
;     int wgid = (int)L; { const int q = nwg / NXCD, r = nwg % NXCD, xcd = wgid % NXCD, off = wgid / NXCD; wgid = (xcd < r ? xcd * (q + 1) : r * (q + 1) + (xcd - r) * q) + off; }
;     const int nig = WGM * nN, gid = wgid / nig, fm = gid * WGM, gsz = (nM - fm) < WGM ? (nM - fm) : WGM;
;     u.pm = fm + ((wgid % nig) % gsz); u.pn = (wgid % nig) / gsz; if (revn) u.pn = nN - 1 - u.pn; return true;
;   }
; DI void xcd_barrier_complete(unsigned* bar, unsigned x, unsigned& nloc, unsigned& nx) {
;   const unsigned G = gridDim.x * gridDim.y * gridDim.z;
;   unsigned sum, cnt, mine, sp = 0u;
;   for (;;) {
;     sum = 0u; cnt = 0u; mine = 0u;
; #pragma unroll
;     for (unsigned j = 0; j < 16; ++j) { const unsigned c = xb_ld(&bar[XB_XCNT(j)]); sum += c; cnt += (c > 0u) ? 1u : 0u; mine = (j == x) ? c : mine; }
;     if (sum == G) break;
;     __builtin_amdgcn_s_sleep(1);
;     if ((++sp & 255u) == 0u) { if (xb_ld(&bar[XB_TMO])) break; if (sp > XB_SPIN_CAP) { atomicAdd(&bar[XB_TMO], 1u); break; } }
;   }
;   nloc = mine > 0u ? mine : 1u; nx = cnt > 0u ? cnt : 1u;
; }
	v_writelane_b32 v241, s64, 52
	s_cmp_eq_u32 s24, 15
	s_cselect_b64 s[66:67], -1, 0
	v_writelane_b32 v241, s65, 53
	v_writelane_b32 v241, s66, 54
	s_cmp_eq_u32 s24, 14
	s_mul_i32 s54, s63, s54
	v_writelane_b32 v241, s67, 55
	s_cselect_b64 s[66:67], -1, 0
	v_writelane_b32 v241, s66, 56
	s_cmp_eq_u32 s24, 13
	s_mul_i32 s45, s62, s45
	v_writelane_b32 v241, s67, 57
	s_cselect_b64 s[66:67], -1, 0
	v_writelane_b32 v241, s66, 58
	s_cmp_eq_u32 s24, 12
	s_mul_i32 s44, s58, s44
	v_writelane_b32 v241, s67, 59
	s_cselect_b64 s[66:67], -1, 0
	v_writelane_b32 v241, s66, 60
	s_cmp_eq_u32 s24, 11
	s_mul_i32 s37, s56, s37
	v_writelane_b32 v241, s67, 61
	s_cselect_b64 s[66:67], -1, 0
	v_writelane_b32 v241, s66, 62
	s_cmp_eq_u32 s24, 10
	s_mul_i32 s35, s51, s35
	v_writelane_b32 v241, s67, 63
	s_cselect_b64 s[66:67], -1, 0
	v_writelane_b32 v240, s66, 0
	s_cmp_eq_u32 s24, 9
	s_mul_i32 s31, s47, s31
	v_writelane_b32 v240, s67, 1
	s_cselect_b64 s[66:67], -1, 0
	v_writelane_b32 v240, s66, 2
	s_cmp_eq_u32 s24, 8
	s_mul_i32 s19, s39, s19
	v_writelane_b32 v240, s67, 3
	s_cselect_b64 s[66:67], -1, 0
	v_writelane_b32 v240, s66, 4
	s_cmp_eq_u32 s24, 7
	s_mul_i32 s18, s34, s18
	v_writelane_b32 v240, s67, 5
	s_cselect_b64 s[66:67], -1, 0
	v_writelane_b32 v240, s66, 6
	s_cmp_eq_u32 s24, 6
	v_mov_b64_e32 v[2:3], s[26:27]
	v_writelane_b32 v240, s67, 7
	s_cselect_b64 s[66:67], -1, 0
	v_writelane_b32 v240, s66, 8
	s_cmp_eq_u32 s24, 5
	v_mov_b64_e32 v[6:7], s[26:27]
	v_writelane_b32 v240, s67, 9
	s_cselect_b64 s[66:67], -1, 0
	v_writelane_b32 v240, s66, 10
	s_cmp_eq_u32 s24, 4
	v_mov_b64_e32 v[10:11], s[26:27]
	v_writelane_b32 v240, s67, 11
	s_cselect_b64 s[66:67], -1, 0
	v_writelane_b32 v240, s66, 12
	s_cmp_eq_u32 s24, 3
	v_mov_b64_e32 v[14:15], s[26:27]
	v_writelane_b32 v240, s67, 13
	s_cselect_b64 s[66:67], -1, 0
	v_writelane_b32 v240, s66, 14
	s_cmp_eq_u32 s24, 2
	v_mov_b32_e32 v145, 0
	v_writelane_b32 v240, s67, 15
	s_cselect_b64 s[66:67], -1, 0
	v_writelane_b32 v240, s66, 16
	s_cmp_eq_u32 s24, 1
	v_mov_b32_e32 v184, 0x358637bd
	v_writelane_b32 v240, s67, 17
	s_cselect_b64 s[66:67], -1, 0
	v_writelane_b32 v240, s66, 18
	s_cmp_eq_u32 s24, 0
	v_mov_b32_e32 v185, 0x1000
	v_writelane_b32 v240, s67, 19
	s_cselect_b64 s[66:67], -1, 0
	s_lshl_b32 s88, s24, 6
	v_writelane_b32 v240, s66, 20
	s_cmp_lt_u32 s4, s89
	v_mov_b32_e32 v186, 0x2000
	v_writelane_b32 v240, s67, 21
	s_cselect_b64 s[66:67], -1, 0
	v_writelane_b32 v240, s66, 22
	s_cmpk_lt_u32 s83, 0x800
	v_mov_b32_e32 v187, 0x3000
	v_writelane_b32 v240, s67, 23
	s_cselect_b64 s[66:67], -1, 0
	s_lshl_b32 s24, s83, 12
	s_and_b32 s24, s24, 0x7000
	s_sub_u32 s94, 0x480, s83
	s_subb_u32 s95, 0, s10
	v_writelane_b32 v240, s66, 24
	s_cmpk_lt_i32 s83, 0x480
	v_mov_b64_e32 v[4:5], s[94:95]
	v_writelane_b32 v240, s67, 25
	s_cselect_b64 s[66:67], -1, 0
	s_add_i32 s54, s54, s16
	v_writelane_b32 v240, s24, 26
	s_mul_hi_i32 s24, s54, 0x38e38e39
	s_lshr_b32 s63, s24, 31
	s_ashr_i32 s24, s24, 4
	s_add_i32 s24, s24, s63
	s_mul_i32 s63, s24, 0x48
	s_sub_i32 s54, s54, s63
	s_bfe_i32 s63, s54, 0x80000
	s_bfe_u32 s63, s63, 0x3000c
	s_add_i32 s74, s54, s63
	s_and_b32 s63, s74, 0xf8
	s_sub_i32 s54, s54, s63
	s_sext_i32_i8 s75, s54
	v_writelane_b32 v240, s66, 27
	s_lshl_b32 s54, s24, 11
	s_lshl_b32 s63, s75, 8
	v_writelane_b32 v240, s67, 28
	s_add_i32 s54, s63, s54
	s_add_i32 s45, s45, s20
	v_writelane_b32 v240, s54, 29
	s_mul_hi_i32 s54, s45, 0x38e38e39
	s_lshr_b32 s62, s54, 31
	s_ashr_i32 s54, s54, 4
	s_add_i32 s54, s54, s62
	s_mul_i32 s62, s54, 0x48
	s_add_i32 s44, s44, s21
	s_sub_i32 s66, s45, s62
	s_mul_hi_i32 s45, s44, 0x38e38e39
	s_lshr_b32 s58, s45, 31
	s_ashr_i32 s45, s45, 4
	s_add_i32 s45, s45, s58
	s_mul_i32 s56, s45, 0x48
	s_add_i32 s37, s37, s22
	s_sub_i32 s62, s44, s56
	s_mul_hi_i32 s44, s37, 0x38e38e39
	s_lshr_b32 s56, s44, 31
	s_ashr_i32 s44, s44, 4
	s_add_i32 s56, s44, s56
	s_mul_i32 s44, s56, 0x48
	s_add_i32 s35, s35, s23
	s_sub_i32 s58, s37, s44
	s_mul_hi_i32 s37, s35, 0x38e38e39
	s_lshr_b32 s44, s37, 31
	s_ashr_i32 s37, s37, 4
	s_add_i32 s37, s37, s44
	s_mul_i32 s44, s37, 0x48
	s_add_i32 s31, s31, s28
	s_sub_i32 s51, s35, s44
	s_mul_hi_i32 s35, s31, 0x38e38e39
	s_lshr_b32 s44, s35, 31
	s_ashr_i32 s35, s35, 4
	s_add_i32 s35, s35, s44
	s_mul_i32 s39, s35, 0x48
	s_add_i32 s19, s19, s29
	s_sub_i32 s44, s31, s39
	s_mul_hi_i32 s31, s19, 0x38e38e39
	s_lshr_b32 s39, s31, 31
	s_ashr_i32 s31, s31, 4
	s_add_i32 s31, s31, s39
	s_mul_i32 s34, s31, 0x48
	s_add_i32 s18, s18, s30
	s_sub_i32 s39, s19, s34
	s_mul_hi_i32 s19, s18, 0x38e38e39
	s_lshr_b32 s34, s19, 31
	s_ashr_i32 s19, s19, 4
	s_add_i32 s19, s19, s34
	s_mul_i32 s34, s19, 0x48
	s_lshl_b32 s71, s54, 3
	s_sub_i32 s34, s18, s34
	s_sub_i32 s18, 0x80, s71
	s_lshl_b32 s69, s45, 3
	s_min_i32 s73, s18, 8
	s_sub_i32 s18, 0x80, s69
	s_lshl_b32 s67, s56, 3
	s_min_i32 s72, s18, 8
	s_sub_i32 s18, 0x80, s67
	s_lshl_b32 s63, s37, 3
	s_min_i32 s70, s18, 8
	s_sub_i32 s18, 0x80, s63
	s_lshl_b32 s54, s35, 3
	s_min_i32 s68, s18, 8
	s_sub_i32 s18, 0x80, s54
	s_lshl_b32 s45, s31, 3
	s_min_i32 s64, s18, 8
	s_sub_i32 s18, 0x80, s45
	s_lshl_b32 s37, s19, 3
	s_min_i32 s56, s18, 8
	s_sub_i32 s18, 0x80, s37
	s_min_i32 s47, s18, 8
	s_lshl_b32 s18, s24, 3
	s_add_i32 s18, s18, s75
	v_writelane_b32 v240, s18, 30
	v_mov_b32_e32 v188, 1
	v_mov_b32_e32 v189, 0xbf4ccccd
	v_writelane_b32 v240, s19, 31
	s_bfe_i32 s18, s74, 0x80000
	s_and_b32 s18, 0xffff, s18
	s_lshr_b32 s18, s18, 3
	s_sub_i32 s18, 8, s18
	s_and_b32 s18, s18, 0xff
	v_writelane_b32 v240, s18, 32
	s_sub_u32 s96, 0x180, s83
	s_subb_u32 s97, 0, s10
	v_writelane_b32 v240, s19, 33
	s_sub_i32 s18, s26, s83
	s_add_i32 s35, s18, 0x17f
	s_cmpk_lt_i32 s83, 0x180
;   DI bool next(int i, Unit& u) const {
;     if ((long)i * G + c >= nwg) return false;
;     const int ii = rev ? ((nwg - c + G - 1) / G - 1 - i) : i;
;     const long L = (long)ii * G + c;
;     int wgid = (int)L; { const int q = nwg / NXCD, r = nwg % NXCD, xcd = wgid % NXCD, off = wgid / NXCD; wgid = (xcd < r ? xcd * (q + 1) : r * (q + 1) + (xcd - r) * q) + off; }
;     const int nig = WGM * nN, gid = wgid / nig, fm = gid * WGM, gsz = (nM - fm) < WGM ? (nM - fm) : WGM;
;     u.pm = fm + ((wgid % nig) % gsz); u.pn = (wgid % nig) / gsz; if (revn) u.pn = nN - 1 - u.pn; return true;
;   }
	s_cselect_b64 s[74:75], -1, 0
	s_sub_u32 vcc_lo, 0x200, s83
	s_subb_u32 vcc_hi, 0, s10
	s_add_i32 s19, s18, 0x1ff
	v_writelane_b32 v240, s74, 34
	s_cmpk_lt_i32 s83, 0x200
	v_mov_b64_e32 v[8:9], s[96:97]
	v_writelane_b32 v240, s75, 35
	s_cselect_b64 s[74:75], -1, 0
	v_writelane_b32 v240, s74, 36
	s_cmpk_lt_u32 s83, 0x400
	v_mov_b64_e32 v[12:13], vcc
	v_writelane_b32 v240, s75, 37
	s_cselect_b64 s[74:75], -1, 0
	s_sub_u32 s84, 0x800, s83
	s_subb_u32 s85, 0, s10
	v_writelane_b32 v240, s74, 38
	s_cmpk_lt_i32 s83, 0x800
	v_mov_b64_e32 v[16:17], s[84:85]
	v_writelane_b32 v240, s75, 39
	s_cselect_b64 s[74:75], -1, 0
	s_add_i32 s10, s17, s16
	s_ashr_i32 s17, s10, 31
	s_lshr_b32 s17, s17, 27
	s_add_i32 s17, s10, s17
	s_and_b32 s24, s17, 0xffe0
	s_sub_i32 s10, s10, s24
	s_bfe_i32 s24, s10, 0x80000
	s_add_i32 s15, s15, s16
	s_bfe_u32 s24, s24, 0x3000c
	s_ashr_i32 s16, s15, 31
	s_add_i32 s24, s10, s24
	s_lshr_b32 s16, s16, 25
	s_and_b32 s31, s24, 0xf8
	s_add_i32 s16, s15, s16
	s_sub_i32 s10, s10, s31
	s_and_b32 s31, s16, 0xff80
	s_sub_i32 s15, s15, s31
	s_bfe_i32 s31, s15, 0x80000
	v_writelane_b32 v240, s74, 40
	s_bfe_u32 s31, s31, 0x3000c
	s_add_i32 s14, s14, s20
	v_writelane_b32 v240, s75, 41
	s_add_i32 s74, s15, s31
	s_and_b32 s31, s74, 0xf8
	s_sub_i32 s15, s15, s31
	s_ashr_i32 s75, s16, 7
	s_sext_i32_i8 s76, s15
	s_lshl_b32 s15, s75, 11
	s_lshl_b32 s16, s76, 8
	s_add_i32 s15, s15, s16
	v_writelane_b32 v240, s15, 42
	s_ashr_i32 s15, s14, 31
	s_lshr_b32 s15, s15, 25
	s_add_i32 s16, s14, s15
	s_and_b32 s15, s16, 0xffffff80
	s_add_i32 s13, s13, s21
	s_sub_i32 s15, s14, s15
	s_ashr_i32 s14, s13, 31
	s_lshr_b32 s14, s14, 25
	s_add_i32 s20, s13, s14
	s_and_b32 s14, s20, 0xffffff80
	s_add_i32 s11, s11, s22
	s_sub_i32 s14, s13, s14
	s_ashr_i32 s13, s11, 31
	s_lshr_b32 s13, s13, 25
	s_add_i32 s13, s11, s13
	s_and_b32 s21, s13, 0xffffff80
	s_add_i32 s9, s9, s23
	s_sub_i32 s11, s11, s21
	s_ashr_i32 s21, s9, 31
	s_lshr_b32 s21, s21, 25
	s_add_i32 s21, s9, s21
	s_abs_i32 s80, s12
	s_and_b32 s22, s21, 0xffffff80
	s_add_i32 s7, s7, s28
	v_cvt_f32_u32_e32 v0, s80
	s_sub_i32 s9, s9, s22
	s_ashr_i32 s22, s7, 31
	s_lshr_b32 s22, s22, 25
	s_add_i32 s77, s7, s22
	s_and_b32 s22, s77, 0xffffff80
	s_add_i32 s6, s6, s29
	v_rcp_iflag_f32_e32 v0, v0
	s_sub_i32 s7, s7, s22
	s_ashr_i32 s22, s6, 31
	s_lshr_b32 s22, s22, 25
	s_add_i32 s78, s6, s22
	s_and_b32 s22, s78, 0xffffff80
	s_add_i32 s5, s5, s30
	v_mul_f32_e32 v0, 0x4f7ffffe, v0
	s_sub_i32 s6, s6, s22
	s_ashr_i32 s22, s5, 31
	v_cvt_u32_f32_e32 v0, v0
	s_lshr_b32 s22, s22, 25
	s_add_i32 s79, s5, s22
	s_and_b32 s22, s79, 0xffffff80
	s_sub_i32 s5, s5, s22
	s_sub_i32 s12, 0, s80
	v_readfirstlane_b32 s22, v0
	s_mul_i32 s12, s12, s22
	s_mul_hi_u32 s12, s22, s12
	s_add_i32 s22, s22, s12
	s_abs_i32 s12, s8
	s_mul_hi_u32 s22, s12, s22
	s_mul_i32 s22, s22, s80
	s_sub_i32 s81, s12, s22
	s_ashr_i32 s12, s17, 5
	s_lshl_b32 s12, s12, 3
	s_sext_i32_i8 s10, s10
	s_add_i32 s86, s12, s10
	s_ashr_i32 s10, s16, 7
	s_lshl_b32 s29, s10, 3
	s_sub_i32 s10, 0x80, s29
	s_min_i32 s31, s10, 8
	s_ashr_i32 s10, s20, 7
	s_bfe_i32 s17, s24, 0x80000
	s_lshl_b32 s24, s10, 3
	s_sub_i32 s10, 0x80, s24
	s_min_i32 s30, s10, 8
	s_ashr_i32 s10, s13, 7
	s_lshl_b32 s22, s10, 3
	s_sub_i32 s10, 0x80, s22
	s_min_i32 s28, s10, 8
	s_ashr_i32 s10, s21, 7
	s_lshl_b32 s20, s10, 3
	s_sub_i32 s10, 0x80, s20
	s_min_i32 s23, s10, 8
	s_ashr_i32 s10, s77, 7
	s_lshl_b32 s16, s10, 3
	s_bfe_i32 s74, s74, 0x80000
	s_sub_i32 s10, 0x80, s16
	s_lshl_b32 s75, s75, 3
	s_sext_i32_i16 s74, s74
	s_min_i32 s21, s10, 8
	s_ashr_i32 s10, s78, 7
	s_add_i32 s78, s75, s76
	s_ashr_i32 s75, s74, 3
	s_lshr_b32 s74, s74, 3
	v_writelane_b32 v240, s75, 43
	s_bfe_i64 s[74:75], s[74:75], 0x100000
	s_lshl_b64 s[74:75], s[74:75], 19
	s_sext_i32_i16 s82, s17
	v_writelane_b32 v240, s74, 44
	s_lshl_b32 s12, s10, 3
	s_sub_i32 s10, 0x80, s12
	v_writelane_b32 v240, s75, 45
	s_ashr_i32 s74, s82, 3
	v_writelane_b32 v240, s74, 46
	s_lshr_b32 s74, s82, 3
	s_bfe_i64 s[74:75], s[74:75], 0x100000
	s_lshl_b64 s[74:75], s[74:75], 19
	v_writelane_b32 v240, s74, 47
	s_mov_b32 s76, s78
	s_min_i32 s17, s10, 8
	v_writelane_b32 v240, s75, 48
	s_ashr_i32 s10, s79, 7
	s_ashr_i32 s79, s78, 31
	v_writelane_b32 v240, s76, 49
	s_lshl_b32 s10, s10, 3
	s_sub_i32 s13, 0x80, s10
	v_writelane_b32 v240, s77, 50
	s_lshl_b64 s[76:77], s[78:79], 19
	v_writelane_b32 v240, s76, 51
	s_ashr_i32 s87, s86, 31
	s_min_i32 s13, s13, 8
	v_writelane_b32 v240, s77, 52
	s_mov_b32 s76, s86
	v_writelane_b32 v240, s76, 53
	s_ashr_i32 s74, s8, 31
	s_add_i32 s8, s92, 0x200
	s_sub_i32 s75, s81, s80
	v_writelane_b32 v240, s77, 54
	s_lshl_b64 s[76:77], s[86:87], 19
	s_cmp_ge_u32 s81, s80
	v_writelane_b32 v240, s76, 55
	s_cselect_b32 s75, s75, s81
	s_mov_b32 s86, s4
	v_writelane_b32 v240, s77, 56
	s_sub_i32 s76, s75, s80
	s_cmp_ge_u32 s75, s80
	s_cselect_b32 s75, s76, s75
	s_xor_b32 s75, s75, s74
	s_sub_i32 s74, s75, s74
	s_add_i32 s74, s74, s59
	s_abs_i32 s59, s65
	v_cvt_f32_u32_e32 v0, s59
	s_sub_i32 s65, 0, s59
	s_lshl_b32 s74, s74, 8
	v_writelane_b32 v240, s74, 57
	v_rcp_iflag_f32_e32 v0, v0
	s_mov_b32 s80, s88
	s_movk_i32 s82, 0x91
	s_movk_i32 s81, 0xc1
	v_mul_f32_e32 v0, 0x4f7ffffe, v0
	v_cvt_u32_f32_e32 v0, v0
	v_bfrev_b32_e32 v190, 0.5
	v_mov_b32_e32 v191, 0x7f800000
	v_mov_b32_e32 v192, 0x1fe
	v_readfirstlane_b32 s75, v0
	s_mul_i32 s65, s65, s75
	s_mul_hi_u32 s65, s75, s65
	s_add_i32 s75, s75, s65
	s_abs_i32 s65, s60
	s_mul_hi_u32 s75, s65, s75
	s_mul_i32 s75, s75, s59
	s_sub_i32 s65, s65, s75
	s_ashr_i32 s60, s60, 31
	s_sub_i32 s74, s65, s59
	s_cmp_ge_u32 s65, s59
	s_cselect_b32 s65, s74, s65
	s_sub_i32 s74, s65, s59
	s_cmp_ge_u32 s65, s59
;   DI bool next(int i, Unit& u) const {
;     if ((long)i * G + c >= nwg) return false;
;     const int ii = rev ? ((nwg - c + G - 1) / G - 1 - i) : i;
;     const long L = (long)ii * G + c;
;     int wgid = (int)L; { const int q = nwg / NXCD, r = nwg % NXCD, xcd = wgid % NXCD, off = wgid / NXCD; wgid = (xcd < r ? xcd * (q + 1) : r * (q + 1) + (xcd - r) * q) + off; }
;     const int nig = WGM * nN, gid = wgid / nig, fm = gid * WGM, gsz = (nM - fm) < WGM ? (nM - fm) : WGM;
;     u.pm = fm + ((wgid % nig) % gsz); u.pn = (wgid % nig) / gsz; if (revn) u.pn = nN - 1 - u.pn; return true;
;   }
	s_cselect_b32 s59, s74, s65
	s_xor_b32 s59, s59, s60
	s_sub_i32 s59, s59, s60
	s_add_i32 s59, s59, s55
	s_abs_i32 s55, s61
	v_cvt_f32_u32_e32 v0, s55
	s_sub_i32 s60, 0, s55
	s_lshl_b32 s59, s59, 8
	v_writelane_b32 v240, s59, 58
	v_rcp_iflag_f32_e32 v0, v0
	v_mov_b32_e32 v193, 0x1de
	v_mov_b32_e32 v194, 0xfffffe2f
	v_mov_b32_e32 v195, 0xf149f2ca
	v_mul_f32_e32 v0, 0x4f7ffffe, v0
	v_cvt_u32_f32_e32 v0, v0
	s_mov_b32 s88, 0x47800000
	v_readfirstlane_b32 s61, v0
	s_mul_i32 s60, s60, s61
	s_mul_hi_u32 s60, s61, s60
	s_add_i32 s61, s61, s60
	s_abs_i32 s60, s53
	s_mul_hi_u32 s61, s60, s61
	s_mul_i32 s61, s61, s55
	s_sub_i32 s60, s60, s61
	s_ashr_i32 s53, s53, 31
	s_sub_i32 s59, s60, s55
	s_cmp_ge_u32 s60, s55
	s_cselect_b32 s59, s59, s60
	s_sub_i32 s60, s59, s55
	s_cmp_ge_u32 s59, s55
	s_cselect_b32 s55, s60, s59
	s_xor_b32 s55, s55, s53
	s_sub_i32 s53, s55, s53
	s_add_i32 s53, s53, s49
	s_abs_i32 s49, s57
	v_cvt_f32_u32_e32 v0, s49
	s_sub_i32 s55, 0, s49
	s_lshl_b32 s53, s53, 8
	v_writelane_b32 v240, s53, 59
	v_rcp_iflag_f32_e32 v0, v0
	s_nop 0
	v_mul_f32_e32 v0, 0x4f7ffffe, v0
	v_cvt_u32_f32_e32 v0, v0
	s_nop 0
	v_readfirstlane_b32 s57, v0
	s_mul_i32 s55, s55, s57
	s_mul_hi_u32 s55, s57, s55
	s_add_i32 s57, s57, s55
	s_abs_i32 s55, s50
	s_mul_hi_u32 s57, s55, s57
	s_mul_i32 s57, s57, s49
	s_sub_i32 s55, s55, s57
	s_ashr_i32 s50, s50, 31
	s_sub_i32 s53, s55, s49
	s_cmp_ge_u32 s55, s49
	s_cselect_b32 s53, s53, s55
	s_sub_i32 s55, s53, s49
	s_cmp_ge_u32 s53, s49
	s_cselect_b32 s49, s55, s53
	s_xor_b32 s49, s49, s50
	s_sub_i32 s49, s49, s50
	s_add_i32 s49, s49, s46
	s_abs_i32 s46, s52
	v_cvt_f32_u32_e32 v0, s46
	s_sub_i32 s50, 0, s46
	s_lshl_b32 s49, s49, 8
	v_writelane_b32 v240, s49, 60
	v_rcp_iflag_f32_e32 v0, v0
	s_nop 0
	v_mul_f32_e32 v0, 0x4f7ffffe, v0
	v_cvt_u32_f32_e32 v0, v0
	s_nop 0
	v_readfirstlane_b32 s52, v0
	s_mul_i32 s50, s50, s52
	s_mul_hi_u32 s50, s52, s50
	s_add_i32 s52, s52, s50
	s_abs_i32 s50, s43
	s_mul_hi_u32 s52, s50, s52
	s_mul_i32 s52, s52, s46
	s_sub_i32 s50, s50, s52
	s_ashr_i32 s43, s43, 31
	s_sub_i32 s49, s50, s46
	s_cmp_ge_u32 s50, s46
	s_cselect_b32 s49, s49, s50
	s_sub_i32 s50, s49, s46
	s_cmp_ge_u32 s49, s46
	s_cselect_b32 s46, s50, s49
	s_xor_b32 s46, s46, s43
	s_sub_i32 s43, s46, s43
	s_add_i32 s43, s43, s42
	s_abs_i32 s42, s48
	v_cvt_f32_u32_e32 v0, s42
	s_sub_i32 s46, 0, s42
	s_lshl_b32 s43, s43, 8
	v_writelane_b32 v240, s43, 61
	v_rcp_iflag_f32_e32 v0, v0
	s_nop 0
	v_mul_f32_e32 v0, 0x4f7ffffe, v0
	v_cvt_u32_f32_e32 v0, v0
	s_nop 0
	v_readfirstlane_b32 s48, v0
	s_mul_i32 s46, s46, s48
	s_mul_hi_u32 s46, s48, s46
	s_add_i32 s48, s48, s46
	s_abs_i32 s46, s40
	s_mul_hi_u32 s48, s46, s48
	s_mul_i32 s48, s48, s42
	s_sub_i32 s46, s46, s48
	s_ashr_i32 s40, s40, 31
	s_sub_i32 s43, s46, s42
	s_cmp_ge_u32 s46, s42
	s_cselect_b32 s43, s43, s46
	s_sub_i32 s46, s43, s42
	s_cmp_ge_u32 s43, s42
	s_cselect_b32 s42, s46, s43
	s_xor_b32 s42, s42, s40
	s_sub_i32 s40, s42, s40
	s_add_i32 s40, s40, s38
	s_abs_i32 s38, s41
	v_cvt_f32_u32_e32 v0, s38
	s_sub_i32 s41, 0, s38
	s_lshl_b32 s40, s40, 8
	v_writelane_b32 v240, s40, 62
	v_rcp_iflag_f32_e32 v0, v0
	s_nop 0
	v_mul_f32_e32 v0, 0x4f7ffffe, v0
	v_cvt_u32_f32_e32 v0, v0
	s_nop 0
	v_readfirstlane_b32 s42, v0
	s_mul_i32 s41, s41, s42
	s_mul_hi_u32 s41, s42, s41
	s_add_i32 s42, s42, s41
	s_abs_i32 s41, s36
	s_mul_hi_u32 s42, s41, s42
	s_mul_i32 s42, s42, s38
	s_sub_i32 s41, s41, s42
	s_ashr_i32 s36, s36, 31
	s_sub_i32 s40, s41, s38
	s_cmp_ge_u32 s41, s38
	s_cselect_b32 s40, s40, s41
	s_sub_i32 s41, s40, s38
	s_cmp_ge_u32 s40, s38
	s_cselect_b32 s38, s41, s40
	s_xor_b32 s38, s38, s36
	s_sub_i32 s36, s38, s36
	s_add_i32 s36, s36, s33
	s_abs_i32 s33, s73
	v_cvt_f32_u32_e32 v0, s33
	s_sub_i32 s38, 0, s33
	s_lshl_b32 s36, s36, 8
	v_writelane_b32 v240, s36, 63
	v_rcp_iflag_f32_e32 v0, v0
	s_ashr_i32 s36, s66, 31
	v_mul_f32_e32 v0, 0x4f7ffffe, v0
	v_cvt_u32_f32_e32 v0, v0
	s_nop 0
	v_readfirstlane_b32 s40, v0
	s_mul_i32 s38, s38, s40
	s_mul_hi_u32 s38, s40, s38
	s_add_i32 s40, s40, s38
	s_abs_i32 s38, s66
	s_mul_hi_u32 s40, s38, s40
	s_mul_i32 s40, s40, s33
	s_sub_i32 s38, s38, s40
	s_sub_i32 s40, s38, s33
	s_cmp_ge_u32 s38, s33
	s_cselect_b32 s38, s40, s38
	s_sub_i32 s40, s38, s33
	s_cmp_ge_u32 s38, s33
	s_cselect_b32 s33, s40, s38
	s_xor_b32 s33, s33, s36
	s_sub_i32 s33, s33, s36
	s_abs_i32 s36, s72
	v_cvt_f32_u32_e32 v0, s36
	s_sub_i32 s38, 0, s36
	s_add_i32 s33, s33, s71
	s_lshl_b32 s33, s33, 8
	v_rcp_iflag_f32_e32 v0, v0
	v_writelane_b32 v239, s33, 0
	s_ashr_i32 s33, s62, 31
	v_mul_f32_e32 v0, 0x4f7ffffe, v0
	v_cvt_u32_f32_e32 v0, v0
	s_nop 0
	v_readfirstlane_b32 s40, v0
	s_mul_i32 s38, s38, s40
	s_mul_hi_u32 s38, s40, s38
	s_add_i32 s40, s40, s38
	s_abs_i32 s38, s62
	s_mul_hi_u32 s40, s38, s40
	s_mul_i32 s40, s40, s36
	s_sub_i32 s38, s38, s40
	s_sub_i32 s40, s38, s36
	s_cmp_ge_u32 s38, s36
	s_cselect_b32 s38, s40, s38
	s_sub_i32 s40, s38, s36
	s_cmp_ge_u32 s38, s36
	s_cselect_b32 s36, s40, s38
	s_xor_b32 s36, s36, s33
	s_sub_i32 s33, s36, s33
	s_abs_i32 s36, s70
	v_cvt_f32_u32_e32 v0, s36
	s_sub_i32 s38, 0, s36
	s_add_i32 s33, s33, s69
	s_lshl_b32 s33, s33, 8
	v_rcp_iflag_f32_e32 v0, v0
	v_writelane_b32 v239, s33, 1
	s_ashr_i32 s33, s58, 31
	v_mul_f32_e32 v0, 0x4f7ffffe, v0
	v_cvt_u32_f32_e32 v0, v0
	s_nop 0
	v_readfirstlane_b32 s40, v0
	s_mul_i32 s38, s38, s40
	s_mul_hi_u32 s38, s40, s38
	s_add_i32 s40, s40, s38
	s_abs_i32 s38, s58
	s_mul_hi_u32 s40, s38, s40
	s_mul_i32 s40, s40, s36
	s_sub_i32 s38, s38, s40
	s_sub_i32 s40, s38, s36
	s_cmp_ge_u32 s38, s36
	s_cselect_b32 s38, s40, s38
	s_sub_i32 s40, s38, s36
	s_cmp_ge_u32 s38, s36
	s_cselect_b32 s36, s40, s38
	s_xor_b32 s36, s36, s33
;   DI bool next(int i, Unit& u) const {
;     if ((long)i * G + c >= nwg) return false;
;     const int ii = rev ? ((nwg - c + G - 1) / G - 1 - i) : i;
;     const long L = (long)ii * G + c;
;     int wgid = (int)L; { const int q = nwg / NXCD, r = nwg % NXCD, xcd = wgid % NXCD, off = wgid / NXCD; wgid = (xcd < r ? xcd * (q + 1) : r * (q + 1) + (xcd - r) * q) + off; }
;     const int nig = WGM * nN, gid = wgid / nig, fm = gid * WGM, gsz = (nM - fm) < WGM ? (nM - fm) : WGM;
;     u.pm = fm + ((wgid % nig) % gsz); u.pn = (wgid % nig) / gsz; if (revn) u.pn = nN - 1 - u.pn; return true;
;   }
; template <int EPI>
; DI void run_gemm(LAS unsigned char* lds, const u16* A, const u16* Bt, int N, int K, const Params& q, const float* rsrc,
;                  const float* ss_in, float* ss_out) {
;     ...
;   if ((EPI == EPI_RESID && K == 4096) || EPI == EPI_UQ || EPI == EPI_UKV) S.rev = 1;
	s_sub_i32 s33, s36, s33
	s_abs_i32 s36, s68
	v_cvt_f32_u32_e32 v0, s36
	s_sub_i32 s38, 0, s36
	s_add_i32 s33, s33, s67
	s_lshl_b32 s33, s33, 8
	v_rcp_iflag_f32_e32 v0, v0
	v_writelane_b32 v239, s33, 2
	s_ashr_i32 s33, s51, 31
	v_mul_f32_e32 v0, 0x4f7ffffe, v0
	v_cvt_u32_f32_e32 v0, v0
	s_nop 0
	v_readfirstlane_b32 s40, v0
	s_mul_i32 s38, s38, s40
	s_mul_hi_u32 s38, s40, s38
	s_add_i32 s40, s40, s38
	s_abs_i32 s38, s51
	s_mul_hi_u32 s40, s38, s40
	s_mul_i32 s40, s40, s36
	s_sub_i32 s38, s38, s40
	s_sub_i32 s40, s38, s36
	s_cmp_ge_u32 s38, s36
	s_cselect_b32 s38, s40, s38
	s_sub_i32 s40, s38, s36
	s_cmp_ge_u32 s38, s36
	s_cselect_b32 s36, s40, s38
	s_xor_b32 s36, s36, s33
	s_sub_i32 s33, s36, s33
	s_abs_i32 s36, s64
	v_cvt_f32_u32_e32 v0, s36
	s_sub_i32 s38, 0, s36
	s_add_i32 s33, s33, s63
	s_lshl_b32 s33, s33, 8
	v_rcp_iflag_f32_e32 v0, v0
	v_writelane_b32 v239, s33, 3
	s_ashr_i32 s33, s44, 31
	s_mov_b32 s51, 0
	v_mul_f32_e32 v0, 0x4f7ffffe, v0
	v_cvt_u32_f32_e32 v0, v0
	s_nop 0
	v_readfirstlane_b32 s40, v0
	s_mul_i32 s38, s38, s40
	s_mul_hi_u32 s38, s40, s38
	s_add_i32 s40, s40, s38
	s_abs_i32 s38, s44
	s_mul_hi_u32 s40, s38, s40
	s_mul_i32 s40, s40, s36
	s_sub_i32 s38, s38, s40
	s_sub_i32 s40, s38, s36
	s_cmp_ge_u32 s38, s36
	s_cselect_b32 s38, s40, s38
	s_sub_i32 s40, s38, s36
	s_cmp_ge_u32 s38, s36
	s_cselect_b32 s36, s40, s38
	s_xor_b32 s36, s36, s33
	s_sub_i32 s33, s36, s33
	s_abs_i32 s36, s56
	v_cvt_f32_u32_e32 v0, s36
	s_sub_i32 s38, 0, s36
	s_add_i32 s33, s33, s54
	s_lshl_b32 s33, s33, 8
	v_rcp_iflag_f32_e32 v0, v0
	v_writelane_b32 v239, s33, 4
	s_ashr_i32 s33, s39, 31
	v_mul_f32_e32 v0, 0x4f7ffffe, v0
	v_cvt_u32_f32_e32 v0, v0
	s_nop 0
	v_readfirstlane_b32 s40, v0
	s_mul_i32 s38, s38, s40
	s_mul_hi_u32 s38, s40, s38
	s_add_i32 s40, s40, s38
	s_abs_i32 s38, s39
	s_mul_hi_u32 s40, s38, s40
	s_mul_i32 s40, s40, s36
	s_sub_i32 s38, s38, s40
	s_sub_i32 s39, s38, s36
	s_cmp_ge_u32 s38, s36
	s_cselect_b32 s38, s39, s38
	s_sub_i32 s39, s38, s36
	s_cmp_ge_u32 s38, s36
	s_cselect_b32 s36, s39, s38
	s_xor_b32 s36, s36, s33
	s_sub_i32 s33, s36, s33
	s_abs_i32 s36, s47
	v_cvt_f32_u32_e32 v0, s36
	s_sub_i32 s38, 0, s36
	s_add_i32 s33, s33, s45
	s_lshl_b32 s33, s33, 8
	v_rcp_iflag_f32_e32 v0, v0
	v_writelane_b32 v239, s33, 5
	s_ashr_i32 s33, s34, 31
	v_mul_f32_e32 v0, 0x4f7ffffe, v0
	v_cvt_u32_f32_e32 v0, v0
	s_nop 0
	v_readfirstlane_b32 s39, v0
	s_mul_i32 s38, s38, s39
	s_mul_hi_u32 s38, s39, s38
	s_add_i32 s39, s39, s38
	s_abs_i32 s38, s34
	s_mul_hi_u32 s39, s38, s39
	s_mul_i32 s39, s39, s36
	s_sub_i32 s38, s38, s39
	s_sub_i32 s34, s38, s36
	s_cmp_ge_u32 s38, s36
	s_cselect_b32 s34, s34, s38
	s_sub_i32 s38, s34, s36
	s_cmp_ge_u32 s34, s36
	s_cselect_b32 s34, s38, s34
	s_xor_b32 s34, s34, s33
	s_sub_i32 s33, s34, s33
	s_add_i32 s36, s33, s37
	s_abs_i32 s33, s26
	v_cvt_f32_u32_e32 v0, s33
	s_sub_i32 s34, 0, s33
	s_lshl_b32 s36, s36, 8
	v_writelane_b32 v239, s36, 6
	v_rcp_iflag_f32_e32 v0, v0
	s_nop 0
	v_mul_f32_e32 v0, 0x4f7ffffe, v0
	v_cvt_u32_f32_e32 v0, v0
	s_nop 0
	v_readfirstlane_b32 s37, v0
	s_mul_i32 s34, s34, s37
	s_mul_hi_u32 s34, s37, s34
	s_add_i32 s34, s37, s34
	s_sub_i32 s37, 0xfffffe81, s18
	s_max_i32 s37, s35, s37
	s_mul_hi_u32 s38, s37, s34
	s_mul_i32 s39, s38, s33
	s_sub_i32 s37, s37, s39
	s_ashr_i32 s35, s35, 31
	s_xor_b32 s35, s35, s27
	s_add_i32 s36, s38, 1
	s_sub_i32 s39, s37, s33
	s_cmp_ge_u32 s37, s33
	s_cselect_b32 s36, s36, s38
	s_cselect_b32 s37, s39, s37
	s_add_i32 s38, s36, 1
	s_cmp_ge_u32 s37, s33
	s_cselect_b32 s36, s38, s36
	s_xor_b32 s36, s36, s35
	s_sub_i32 s35, s36, s35
	v_writelane_b32 v239, s35, 7
	s_add_i32 s35, s35, -1
	s_mul_i32 s35, s35, s26
	s_add_i32 s36, s35, s83
	s_ashr_i32 s37, s36, 31
	s_lshr_b32 s37, s37, 29
	s_add_i32 s37, s36, s37
	s_and_b32 s38, s37, -8
	s_sub_i32 s36, s36, s38
	s_ashr_i32 s37, s37, 3
	s_cmp_lt_i32 s36, 0
	s_cselect_b32 s38, 49, 48
	s_mul_i32 s36, s38, s36
	s_add_i32 s36, s36, s37
	s_mul_hi_i32 s37, s36, 0x2aaaaaab
	s_lshr_b32 s38, s37, 31
	s_ashr_i32 s37, s37, 2
	s_add_i32 s37, s37, s38
	s_mul_i32 s38, s37, 24
	s_lshl_b32 s37, s37, 3
	s_sub_i32 s36, s36, s38
	s_sub_i32 s38, 0x80, s37
	s_min_i32 s38, s38, 8
	s_abs_i32 s39, s38
	v_cvt_f32_u32_e32 v0, s39
	s_sub_i32 s40, 0, s39
	s_ashr_i32 s43, s38, 31
	v_rcp_iflag_f32_e32 v0, v0
	s_nop 0
	v_mul_f32_e32 v0, 0x4f7ffffe, v0
	v_cvt_u32_f32_e32 v0, v0
	s_nop 0
	v_readfirstlane_b32 s41, v0
	s_mul_i32 s40, s40, s41
	s_mul_hi_u32 s40, s41, s40
	s_add_i32 s41, s41, s40
	s_abs_i32 s40, s36
	s_mul_hi_u32 s41, s40, s41
	s_mul_i32 s42, s41, s39
	s_sub_i32 s40, s40, s42
	s_ashr_i32 s42, s36, 31
	s_sub_i32 s44, s40, s39
	s_add_i32 s45, s41, 1
	s_cmp_ge_u32 s40, s39
	s_cselect_b32 s40, s44, s40
	s_cselect_b32 s41, s45, s41
	s_sub_i32 s44, s40, s39
	s_add_i32 s45, s41, 1
	s_cmp_ge_u32 s40, s39
	s_cselect_b32 s39, s44, s40
	s_cselect_b32 s40, s45, s41
	s_sub_i32 s35, s35, s26
	s_add_i32 s41, s35, s83
	s_ashr_i32 s44, s41, 31
	s_xor_b32 s39, s39, s42
	s_lshr_b32 s44, s44, 29
	s_sub_i32 s39, s39, s42
	s_add_i32 s44, s41, s44
	s_add_i32 s39, s37, s39
	s_and_b32 s45, s44, -8
	s_lshl_b32 s39, s39, 8
	s_sub_i32 s41, s41, s45
	v_writelane_b32 v239, s39, 8
	s_ashr_i32 s39, s44, 3
	s_cmp_lt_i32 s41, 0
	s_cselect_b32 s44, 49, 48
	s_mul_i32 s41, s44, s41
	s_add_i32 s41, s41, s39
	s_mul_hi_i32 s39, s41, 0x2aaaaaab
	s_lshr_b32 s44, s39, 31
	s_ashr_i32 s39, s39, 2
	s_add_i32 s39, s39, s44
	s_mul_i32 s44, s39, 24
	s_lshl_b32 s39, s39, 3
	s_sub_i32 s41, s41, s44
	s_sub_i32 s44, 0x80, s39
	s_min_i32 s44, s44, 8
	s_abs_i32 s44, s44
	v_cvt_f32_u32_e32 v0, s44
	s_sub_i32 s45, 0, s44
	v_rcp_iflag_f32_e32 v0, v0
	s_nop 0
	v_mul_f32_e32 v0, 0x4f7ffffe, v0
;   DI bool next(int i, Unit& u) const {
;     if ((long)i * G + c >= nwg) return false;
;     const int ii = rev ? ((nwg - c + G - 1) / G - 1 - i) : i;
;     const long L = (long)ii * G + c;
;     int wgid = (int)L; { const int q = nwg / NXCD, r = nwg % NXCD, xcd = wgid % NXCD, off = wgid / NXCD; wgid = (xcd < r ? xcd * (q + 1) : r * (q + 1) + (xcd - r) * q) + off; }
;     const int nig = WGM * nN, gid = wgid / nig, fm = gid * WGM, gsz = (nM - fm) < WGM ? (nM - fm) : WGM;
;     u.pm = fm + ((wgid % nig) % gsz); u.pn = (wgid % nig) / gsz; if (revn) u.pn = nN - 1 - u.pn; return true;
;   }
; template <int EPI>
; DI void run_gemm(LAS unsigned char* lds, const u16* A, const u16* Bt, int N, int K, const Params& q, const float* rsrc,
;                  const float* ss_in, float* ss_out) {
;     ...
;   if ((EPI == EPI_RESID && K == 4096) || EPI == EPI_UQ || EPI == EPI_UKV) S.rev = 1;
	v_cvt_u32_f32_e32 v0, v0
	s_nop 0
	v_readfirstlane_b32 s46, v0
	s_mul_i32 s45, s45, s46
	s_mul_hi_u32 s45, s46, s45
	s_add_i32 s46, s46, s45
	s_abs_i32 s45, s41
	s_mul_hi_u32 s46, s45, s46
	s_mul_i32 s46, s46, s44
	s_sub_i32 s45, s45, s46
	s_ashr_i32 s41, s41, 31
	s_sub_i32 s46, s45, s44
	s_cmp_ge_u32 s45, s44
	s_cselect_b32 s45, s46, s45
	s_sub_i32 s46, s45, s44
	s_cmp_ge_u32 s45, s44
	s_cselect_b32 s44, s46, s45
	s_xor_b32 s44, s44, s41
	s_sub_i32 s41, s44, s41
	s_sub_i32 s35, s35, s26
	s_add_i32 s41, s41, s39
	s_add_i32 s39, s35, s83
	s_ashr_i32 s44, s39, 31
	s_lshr_b32 s44, s44, 29
	s_add_i32 s44, s39, s44
	s_and_b32 s45, s44, -8
	s_lshl_b32 s41, s41, 8
	s_sub_i32 s39, s39, s45
	v_writelane_b32 v239, s41, 9
	s_ashr_i32 s41, s44, 3
	s_cmp_lt_i32 s39, 0
	s_cselect_b32 s44, 49, 48
	s_mul_i32 s39, s44, s39
	s_add_i32 s39, s39, s41
	s_mul_hi_i32 s41, s39, 0x2aaaaaab
	s_lshr_b32 s44, s41, 31
	s_ashr_i32 s41, s41, 2
	s_add_i32 s41, s41, s44
	s_mul_i32 s44, s41, 24
	s_lshl_b32 s41, s41, 3
	s_sub_i32 s39, s39, s44
	s_sub_i32 s44, 0x80, s41
	s_min_i32 s44, s44, 8
	s_abs_i32 s44, s44
	v_cvt_f32_u32_e32 v0, s44
	s_sub_i32 s45, 0, s44
	v_rcp_iflag_f32_e32 v0, v0
	s_nop 0
	v_mul_f32_e32 v0, 0x4f7ffffe, v0
	v_cvt_u32_f32_e32 v0, v0
	s_nop 0
	v_readfirstlane_b32 s46, v0
	s_mul_i32 s45, s45, s46
	s_mul_hi_u32 s45, s46, s45
	s_add_i32 s46, s46, s45
	s_abs_i32 s45, s39
	s_mul_hi_u32 s46, s45, s46
	s_mul_i32 s46, s46, s44
	s_sub_i32 s45, s45, s46
	s_ashr_i32 s39, s39, 31
	s_sub_i32 s46, s45, s44
	s_cmp_ge_u32 s45, s44
	s_cselect_b32 s45, s46, s45
	s_sub_i32 s46, s45, s44
	s_cmp_ge_u32 s45, s44
	s_cselect_b32 s44, s46, s45
	s_xor_b32 s44, s44, s39
	s_sub_i32 s35, s35, s26
	s_sub_i32 s39, s44, s39
	s_add_i32 s35, s35, s83
	s_add_i32 s39, s39, s41
	s_ashr_i32 s41, s35, 31
	s_lshr_b32 s41, s41, 29
	s_add_i32 s41, s35, s41
	s_and_b32 s44, s41, -8
	s_lshl_b32 s39, s39, 8
	s_sub_i32 s35, s35, s44
	v_writelane_b32 v239, s39, 10
	s_ashr_i32 s39, s41, 3
	s_cmp_lt_i32 s35, 0
	s_cselect_b32 s41, 49, 48
	s_mul_i32 s35, s41, s35
	s_add_i32 s35, s35, s39
	s_mul_hi_i32 s39, s35, 0x2aaaaaab
	s_lshr_b32 s41, s39, 31
	s_ashr_i32 s39, s39, 2
	s_add_i32 s39, s39, s41
	s_mul_i32 s41, s39, 24
	s_lshl_b32 s39, s39, 3
	s_sub_i32 s35, s35, s41
	s_sub_i32 s41, 0x80, s39
	s_min_i32 s41, s41, 8
	s_abs_i32 s41, s41
	v_cvt_f32_u32_e32 v0, s41
	s_sub_i32 s44, 0, s41
	v_rcp_iflag_f32_e32 v0, v0
	s_nop 0
	v_mul_f32_e32 v0, 0x4f7ffffe, v0
	v_cvt_u32_f32_e32 v0, v0
	s_nop 0
	v_readfirstlane_b32 s45, v0
	s_mul_i32 s44, s44, s45
	s_mul_hi_u32 s44, s45, s44
	s_add_i32 s45, s45, s44
	s_abs_i32 s44, s35
	s_mul_hi_u32 s45, s44, s45
	s_mul_i32 s45, s45, s41
	s_sub_i32 s44, s44, s45
	s_ashr_i32 s35, s35, 31
	s_sub_i32 s45, s44, s41
	s_cmp_ge_u32 s44, s41
	s_cselect_b32 s44, s45, s44
	s_sub_i32 s45, s44, s41
	s_cmp_ge_u32 s44, s41
	s_cselect_b32 s41, s45, s44
	s_xor_b32 s41, s41, s35
	s_sub_i32 s35, s41, s35
	s_add_i32 s35, s35, s39
	s_xor_b32 s39, s42, s43
	s_xor_b32 s40, s40, s39
	s_sub_i32 s39, s40, s39
	s_mul_i32 s38, s39, s38
	s_sub_i32 s36, s36, s38
	s_sub_i32 s18, 0xfffffe01, s18
	v_writelane_b32 v239, s39, 11
	s_add_i32 s36, s37, s36
	s_max_i32 s18, s19, s18
	v_writelane_b32 v239, s36, 12
	s_mul_hi_u32 s36, s18, s34
	s_mul_i32 s37, s36, s33
	s_sub_i32 s18, s18, s37
	s_lshl_b32 s35, s35, 8
	s_ashr_i32 s19, s19, 31
	v_writelane_b32 v239, s35, 13
	s_xor_b32 s37, s19, s27
	s_add_i32 s19, s36, 1
	s_sub_i32 s35, s18, s33
	s_cmp_ge_u32 s18, s33
	s_cselect_b32 s19, s19, s36
	s_cselect_b32 s18, s35, s18
	s_add_i32 s35, s19, 1
	s_cmp_ge_u32 s18, s33
	s_cselect_b32 s18, s35, s19
	s_xor_b32 s38, s18, s37
	s_sub_i32 s18, s38, s37
	v_writelane_b32 v239, s18, 14
	s_add_i32 s18, s18, -1
	s_mul_i32 s19, s18, s26
	s_add_i32 s18, s19, s83
	s_ashr_i32 s35, s18, 31
	s_lshr_b32 s35, s35, 29
	s_add_i32 s35, s18, s35
	s_and_b32 s36, s35, -8
	s_sub_i32 s18, s18, s36
	s_ashr_i32 s35, s35, 3
	s_cmp_gt_i32 s18, -1
	v_writelane_b32 v239, s35, 15
	s_cselect_b64 s[40:41], -1, 0
	s_sub_i32 s35, s19, s26
	s_add_i32 s19, s35, s83
	s_ashr_i32 s36, s19, 31
	s_lshr_b32 s36, s36, 29
	v_writelane_b32 v239, s40, 16
	s_add_i32 s36, s19, s36
	s_and_b32 s39, s36, -8
	v_writelane_b32 v239, s41, 17
	s_ashr_i32 s36, s36, 3
	s_sub_i32 s19, s19, s39
	v_writelane_b32 v239, s36, 18
	s_lshl_b32 s36, s18, 6
	s_cmp_lt_i32 s19, 0
	v_writelane_b32 v239, s36, 19
	s_cselect_b64 s[40:41], -1, 0
	s_sub_i32 s36, s35, s26
	s_add_i32 s35, s36, s83
	s_ashr_i32 s39, s35, 31
	s_lshr_b32 s39, s39, 29
	v_writelane_b32 v239, s40, 20
	s_add_i32 s39, s35, s39
	s_nop 0
	v_writelane_b32 v239, s41, 21
	s_and_b32 s40, s39, -8
	s_ashr_i32 s39, s39, 3
	s_sub_i32 s35, s35, s40
	v_writelane_b32 v239, s39, 22
	s_lshl_b32 s39, s19, 6
	s_cmp_lt_i32 s35, 0
	s_cselect_b64 s[40:41], -1, 0
	s_sub_i32 s36, s36, s26
	s_add_i32 s36, s36, s83
	v_writelane_b32 v239, s39, 23
	s_ashr_i32 s39, s36, 31
	s_lshr_b32 s39, s39, 29
	v_writelane_b32 v239, s40, 24
	s_add_i32 s39, s36, s39
	s_nop 0
	v_writelane_b32 v239, s41, 25
	s_and_b32 s40, s39, -8
	s_ashr_i32 s39, s39, 3
	s_sub_i32 s36, s36, s40
	v_writelane_b32 v239, s39, 26
	s_lshl_b32 s39, s35, 6
	s_cmp_lt_i32 s36, 0
	s_cselect_b64 s[40:41], -1, 0
	s_abs_i32 s31, s31
	v_cvt_f32_u32_e32 v0, s31
	v_writelane_b32 v239, s39, 27
	v_writelane_b32 v239, s40, 28
	s_sub_i32 s39, 0, s31
	v_rcp_iflag_f32_e32 v0, v0
	v_writelane_b32 v239, s41, 29
	v_mul_f32_e32 v0, 0x4f7ffffe, v0
	v_cvt_u32_f32_e32 v0, v0
	s_nop 0
	v_readfirstlane_b32 s40, v0
	s_mul_i32 s39, s39, s40
	s_mul_hi_u32 s39, s40, s39
	s_add_i32 s40, s40, s39
	s_abs_i32 s39, s15
	s_mul_hi_u32 s40, s39, s40
	s_mul_i32 s40, s40, s31
	s_sub_i32 s39, s39, s40
	s_lshl_b32 s40, s36, 6
; DI void prep_wt(const float* __restrict__ src, u16* __restrict__ dst, int K, int N, int Npad,
;                 const float* __restrict__ gain, float* tile) {
;     ...
;   for (int t0 = blockIdx.x; t0 < nt4; t0 += 4 * gridDim.x) {
;     f32x4 v[4][2];
; #pragma unroll
;     for (int j = 0; j < 4; ++j) {
;       const int t = t0 + j * gridDim.x;
;       const int kt = t % tk, nt = t / tk;
; #pragma unroll
;       for (int i = 0; i < 2; ++i) {
;         const int e = tid + NTHR * i; const int kk = e >> 4, n4 = (e & 15) * 4; const int n = nt * 64 + n4;
;         v[j][i] = (f32x4){0.f, 0.f, 0.f, 0.f};
;         if (t < nt4 && n < N) {
;           v[j][i] = *(const f32x4*)(src + (size_t)(kt * 64 + kk) * N + n);
;           if (gain) v[j][i] *= gain[kt * 64 + kk];
	s_ashr_i32 s15, s15, 31
	v_writelane_b32 v239, s40, 30
	s_sub_i32 s40, s39, s31
	s_cmp_ge_u32 s39, s31
	s_cselect_b32 s39, s40, s39
	s_sub_i32 s40, s39, s31
	s_cmp_ge_u32 s39, s31
	s_cselect_b32 s31, s40, s39
	s_xor_b32 s31, s31, s15
	s_sub_i32 s15, s31, s15
	s_add_i32 s29, s29, s15
	s_abs_i32 s15, s30
	v_cvt_f32_u32_e32 v0, s15
	s_sub_i32 s30, 0, s15
	s_lshl_b32 s29, s29, 8
	v_writelane_b32 v239, s29, 31
	v_rcp_iflag_f32_e32 v0, v0
	s_nop 0
	v_mul_f32_e32 v0, 0x4f7ffffe, v0
	v_cvt_u32_f32_e32 v0, v0
	s_nop 0
	v_readfirstlane_b32 s31, v0
	s_mul_i32 s30, s30, s31
	s_mul_hi_u32 s30, s31, s30
	s_add_i32 s31, s31, s30
	s_abs_i32 s30, s14
	s_mul_hi_u32 s31, s30, s31
	s_mul_i32 s31, s31, s15
	s_sub_i32 s30, s30, s31
	s_ashr_i32 s14, s14, 31
	s_sub_i32 s29, s30, s15
	s_cmp_ge_u32 s30, s15
	s_cselect_b32 s29, s29, s30
	s_sub_i32 s30, s29, s15
	s_cmp_ge_u32 s29, s15
	s_cselect_b32 s15, s30, s29
	s_xor_b32 s15, s15, s14
	s_sub_i32 s14, s15, s14
	s_add_i32 s24, s24, s14
	s_abs_i32 s14, s28
	v_cvt_f32_u32_e32 v0, s14
	s_sub_i32 s15, 0, s14
	s_lshl_b32 s24, s24, 8
	v_writelane_b32 v239, s24, 32
	v_rcp_iflag_f32_e32 v0, v0
	s_mov_b64 s[30:31], vcc
	v_mul_f32_e32 v0, 0x4f7ffffe, v0
	v_cvt_u32_f32_e32 v0, v0
	s_nop 0
	v_readfirstlane_b32 s28, v0
	s_mul_i32 s15, s15, s28
	s_mul_hi_u32 s15, s28, s15
	s_add_i32 s28, s28, s15
	s_abs_i32 s15, s11
	s_mul_hi_u32 s28, s15, s28
	s_mul_i32 s28, s28, s14
	s_sub_i32 s15, s15, s28
	s_ashr_i32 s11, s11, 31
	s_sub_i32 s24, s15, s14
	s_cmp_ge_u32 s15, s14
	s_cselect_b32 s15, s24, s15
	s_sub_i32 s24, s15, s14
	s_cmp_ge_u32 s15, s14
	s_cselect_b32 s14, s24, s15
	s_xor_b32 s14, s14, s11
	s_sub_i32 s11, s14, s11
	s_add_i32 s22, s22, s11
	s_abs_i32 s11, s23
	v_cvt_f32_u32_e32 v0, s11
	s_sub_i32 s14, 0, s11
	v_rcp_iflag_f32_e32 v0, v0
	s_nop 0
	v_mul_f32_e32 v0, 0x4f7ffffe, v0
	v_cvt_u32_f32_e32 v0, v0
	s_nop 0
	v_readfirstlane_b32 s15, v0
	s_mul_i32 s14, s14, s15
	s_mul_hi_u32 s14, s15, s14
	s_add_i32 s15, s15, s14
	s_abs_i32 s14, s9
	s_mul_hi_u32 s15, s14, s15
	s_mul_i32 s15, s15, s11
	s_sub_i32 s14, s14, s15
	s_lshl_b32 s15, s22, 8
	v_writelane_b32 v239, s15, 33
	s_ashr_i32 s9, s9, 31
	s_sub_i32 s15, s14, s11
	s_cmp_ge_u32 s14, s11
	s_cselect_b32 s14, s15, s14
	s_sub_i32 s15, s14, s11
	s_cmp_ge_u32 s14, s11
	s_cselect_b32 s11, s15, s14
	s_xor_b32 s11, s11, s9
	s_sub_i32 s9, s11, s9
	s_add_i32 s20, s20, s9
	s_abs_i32 s9, s21
	v_cvt_f32_u32_e32 v0, s9
	s_sub_i32 s11, 0, s9
	v_rcp_iflag_f32_e32 v0, v0
	s_nop 0
	v_mul_f32_e32 v0, 0x4f7ffffe, v0
	v_cvt_u32_f32_e32 v0, v0
	s_nop 0
	v_readfirstlane_b32 s14, v0
	s_mul_i32 s11, s11, s14
	s_mul_hi_u32 s11, s14, s11
	s_add_i32 s14, s14, s11
	s_abs_i32 s11, s7
	s_mul_hi_u32 s14, s11, s14
	s_mul_i32 s14, s14, s9
	s_sub_i32 s11, s11, s14
	s_lshl_b32 s14, s20, 8
	v_writelane_b32 v239, s14, 34
	s_ashr_i32 s7, s7, 31
	s_sub_i32 s14, s11, s9
	s_cmp_ge_u32 s11, s9
	s_cselect_b32 s11, s14, s11
	s_sub_i32 s14, s11, s9
	s_cmp_ge_u32 s11, s9
	s_cselect_b32 s9, s14, s11
	s_xor_b32 s9, s9, s7
	s_sub_i32 s7, s9, s7
	s_add_i32 s16, s16, s7
	s_abs_i32 s7, s17
	v_cvt_f32_u32_e32 v0, s7
	s_sub_i32 s9, 0, s7
	v_cmp_lt_i64_e64 s[14:15], s[0:1], v[4:5]
	v_rcp_iflag_f32_e32 v0, v0
	s_nop 0
	v_mul_f32_e32 v0, 0x4f7ffffe, v0
	v_cvt_u32_f32_e32 v0, v0
	s_nop 0
	v_readfirstlane_b32 s11, v0
	s_mul_i32 s9, s9, s11
	s_mul_hi_u32 s9, s11, s9
	s_add_i32 s11, s11, s9
	s_abs_i32 s9, s6
	s_mul_hi_u32 s11, s9, s11
	s_mul_i32 s11, s11, s7
	s_sub_i32 s9, s9, s11
	s_lshl_b32 s11, s16, 8
	v_writelane_b32 v239, s11, 35
	s_ashr_i32 s6, s6, 31
	s_sub_i32 s11, s9, s7
	s_cmp_ge_u32 s9, s7
	s_cselect_b32 s9, s11, s9
	s_sub_i32 s11, s9, s7
	s_cmp_ge_u32 s9, s7
	s_cselect_b32 s7, s11, s9
	s_xor_b32 s7, s7, s6
	s_sub_i32 s6, s7, s6
	s_add_i32 s12, s12, s6
	s_abs_i32 s6, s13
	v_cvt_f32_u32_e32 v0, s6
	s_sub_i32 s7, 0, s6
	s_mul_hi_i32 s11, s26, 7
	v_rcp_iflag_f32_e32 v0, v0
	s_nop 0
	v_mul_f32_e32 v0, 0x4f7ffffe, v0
	v_cvt_u32_f32_e32 v0, v0
	s_nop 0
	v_readfirstlane_b32 s9, v0
	s_mul_i32 s7, s7, s9
	s_mul_hi_u32 s7, s9, s7
	s_add_i32 s9, s9, s7
	s_abs_i32 s7, s5
	s_mul_hi_u32 s9, s7, s9
	s_mul_i32 s9, s9, s6
	s_sub_i32 s7, s7, s9
	s_lshl_b32 s9, s12, 8
	v_writelane_b32 v239, s9, 36
	s_ashr_i32 s5, s5, 31
	s_sub_i32 s9, s7, s6
	s_cmp_ge_u32 s7, s6
	s_cselect_b32 s7, s9, s7
	s_sub_i32 s9, s7, s6
	s_cmp_ge_u32 s7, s6
	s_cselect_b32 s6, s9, s7
	s_xor_b32 s6, s6, s5
	s_sub_i32 s5, s6, s5
	s_add_i32 s10, s10, s5
	s_not_b32 s5, s37
	s_add_i32 s5, s5, s38
	s_mul_i32 s5, s5, s26
	s_add_i32 s5, s5, s83
	s_ashr_i32 s6, s5, 31
	s_lshr_b32 s6, s6, 29
	s_add_i32 s6, s5, s6
	s_and_b32 s7, s6, -8
	s_sub_i32 s12, s5, s7
	s_lshl_b32 s5, s10, 8
	v_writelane_b32 v239, s5, 37
	s_ashr_i32 s5, s6, 3
	s_cmp_gt_i32 s12, -1
	s_cselect_b64 s[6:7], -1, 0
	s_sub_i32 s4, 0xfffffe00, s92
	v_writelane_b32 v239, s5, 38
	s_max_i32 s4, s8, s4
	v_writelane_b32 v239, s6, 39
	s_mul_hi_u32 s5, s4, s34
	v_mov_b64_e32 v[0:1], s[26:27]
	v_writelane_b32 v239, s7, 40
	s_mul_i32 s6, s5, s33
	s_sub_i32 s4, s4, s6
	s_ashr_i32 s6, s8, 31
	s_lshl_b32 s7, s12, 6
	s_xor_b32 s6, s6, s27
	v_writelane_b32 v239, s7, 41
	s_add_i32 s7, s5, 1
	s_sub_i32 s8, s4, s33
	s_cmp_ge_u32 s4, s33
	s_cselect_b32 s4, s8, s4
	v_readlane_b32 s8, v241, 47
	v_readlane_b32 s9, v241, 48
	s_cselect_b32 s5, s7, s5
	s_add_i32 s7, s5, 1
	v_cndmask_b32_e64 v183, 0, 1, s[8:9]
	v_cmp_gt_i64_e64 s[8:9], s[90:91], v[0:1]
; DI void prep_wt(const float* __restrict__ src, u16* __restrict__ dst, int K, int N, int Npad,
;                 const float* __restrict__ gain, float* tile) {
;     ...
;   for (int t0 = blockIdx.x; t0 < nt4; t0 += 4 * gridDim.x) {
;     f32x4 v[4][2];
; #pragma unroll
;     for (int j = 0; j < 4; ++j) {
;       const int t = t0 + j * gridDim.x;
;       const int kt = t % tk, nt = t / tk;
; #pragma unroll
;       for (int i = 0; i < 2; ++i) {
;         const int e = tid + NTHR * i; const int kk = e >> 4, n4 = (e & 15) * 4; const int n = nt * 64 + n4;
;         v[j][i] = (f32x4){0.f, 0.f, 0.f, 0.f};
;         if (t < nt4 && n < N) {
;           v[j][i] = *(const f32x4*)(src + (size_t)(kt * 64 + kk) * N + n);
;           if (gain) v[j][i] *= gain[kt * 64 + kk];
	s_cmp_ge_u32 s4, s33
	s_cselect_b32 s4, s7, s5
	v_writelane_b32 v239, s8, 42
	s_xor_b32 s4, s4, s6
	s_sub_i32 s4, s4, s6
	v_writelane_b32 v239, s9, 43
	v_writelane_b32 v239, s90, 44
	s_mul_hi_i32 s5, s26, 3
	s_mul_hi_i32 s7, s26, 5
	v_mov_b64_e32 v[0:1], s[90:91]
	v_writelane_b32 v239, s91, 45
	v_cmp_lt_i64_e64 s[8:9], s[0:1], v[0:1]
	s_mul_i32 s6, s26, 5
	s_mul_i32 s10, s26, 7
	v_writelane_b32 v239, s8, 46
	s_movk_i32 s33, 0xffe0
	s_nop 0
	v_writelane_b32 v239, s9, 47
	v_writelane_b32 v239, s4, 48
	v_writelane_b32 v239, s14, 49
	s_mul_i32 s4, s26, 3
	s_mul_hi_i32 s9, s26, 6
	v_writelane_b32 v239, s15, 50
	v_cmp_lt_i64_e64 s[14:15], s[0:1], v[8:9]
	s_mul_i32 s8, s26, 6
	s_nop 0
	v_writelane_b32 v239, s14, 51
	s_nop 1
	v_writelane_b32 v239, s15, 52
	v_cmp_lt_i64_e64 s[14:15], s[0:1], v[12:13]
	v_cmp_lt_i64_e64 s[0:1], s[0:1], v[16:17]
	s_nop 0
	v_writelane_b32 v239, s14, 53
	s_nop 1
	v_writelane_b32 v239, s15, 54
	v_writelane_b32 v239, s0, 55
	s_nop 1
	v_writelane_b32 v239, s1, 56
	v_cmp_lt_i64_e64 s[0:1], s[4:5], v[0:1]
	s_nop 1
	v_writelane_b32 v239, s0, 57
	s_nop 1
	v_writelane_b32 v239, s1, 58
	v_cmp_lt_i64_e64 s[0:1], s[4:5], v[4:5]
	s_nop 1
	v_writelane_b32 v239, s0, 59
	s_nop 1
	v_writelane_b32 v239, s1, 60
	v_cmp_lt_i64_e64 s[0:1], s[4:5], v[8:9]
	s_nop 1
	v_writelane_b32 v239, s0, 61
	s_nop 1
	v_writelane_b32 v239, s1, 62
	v_cmp_lt_i64_e64 s[0:1], s[4:5], v[12:13]
	s_nop 1
	v_writelane_b32 v239, s0, 63
	s_nop 1
	v_writelane_b32 v238, s1, 0
	v_cmp_lt_i64_e64 s[0:1], s[4:5], v[16:17]
	s_nop 1
	v_writelane_b32 v238, s0, 1
	s_nop 1
	v_writelane_b32 v238, s1, 2
	v_cmp_lt_i64_e64 s[0:1], s[2:3], v[0:1]
	s_nop 1
	v_writelane_b32 v238, s0, 3
	s_nop 1
	v_writelane_b32 v238, s1, 4
	v_cmp_lt_i64_e64 s[0:1], s[2:3], v[4:5]
	s_nop 1
	v_writelane_b32 v238, s0, 5
	s_nop 1
	v_writelane_b32 v238, s1, 6
	v_cmp_lt_i64_e64 s[0:1], s[2:3], v[16:17]
	s_nop 1
	v_writelane_b32 v238, s0, 7
	s_nop 1
	v_writelane_b32 v238, s1, 8
	v_cmp_lt_i64_e64 s[0:1], s[6:7], v[0:1]
	s_nop 1
	v_writelane_b32 v238, s0, 9
	s_nop 1
	v_writelane_b32 v238, s1, 10
	v_cmp_lt_i64_e64 s[0:1], s[6:7], v[4:5]
	s_nop 1
	v_writelane_b32 v238, s0, 11
	s_nop 1
	v_writelane_b32 v238, s1, 12
	v_cmp_lt_i64_e64 s[0:1], s[6:7], v[16:17]
	s_nop 1
	v_writelane_b32 v238, s0, 13
	s_nop 1
	v_writelane_b32 v238, s1, 14
	v_cmp_lt_i64_e64 s[0:1], s[8:9], v[0:1]
	s_nop 1
	v_writelane_b32 v238, s0, 15
	s_nop 1
	v_writelane_b32 v238, s1, 16
	v_cmp_lt_i64_e64 s[0:1], s[8:9], v[4:5]
	s_nop 1
	v_writelane_b32 v238, s0, 17
	s_nop 1
	v_writelane_b32 v238, s1, 18
	v_cmp_lt_i64_e64 s[0:1], s[8:9], v[16:17]
	s_brev_b32 s8, 1
	s_nop 0
	v_writelane_b32 v238, s0, 19
	s_nop 1
	v_writelane_b32 v238, s1, 20
	v_cmp_lt_i64_e64 s[0:1], s[10:11], v[0:1]
	s_nop 1
	v_writelane_b32 v238, s0, 21
	s_nop 1
	v_writelane_b32 v238, s1, 22
	v_cmp_lt_i64_e64 s[0:1], s[10:11], v[4:5]
	s_nop 1
	v_writelane_b32 v238, s0, 23
	s_nop 1
	v_writelane_b32 v238, s1, 24
	v_cmp_lt_i64_e64 s[0:1], s[10:11], v[16:17]
	s_nop 1
	v_writelane_b32 v238, s0, 25
	s_nop 1
	v_writelane_b32 v238, s1, 26
	s_mul_i32 s0, s18, 0x41
	v_writelane_b32 v238, s0, 27
	s_mul_i32 s0, s19, 0x41
	v_writelane_b32 v238, s0, 28
	s_mul_i32 s0, s35, 0x41
	v_writelane_b32 v238, s0, 29
	s_mul_i32 s0, s36, 0x41
	v_writelane_b32 v238, s0, 30
	s_mul_i32 s0, s12, 0x41
	v_writelane_b32 v238, s0, 31
	s_lshl_b32 s0, s86, 7
	v_writelane_b32 v238, s0, 32
	s_lshl_b32 s0, s89, 7
	v_writelane_b32 v238, s0, 33
	v_readlane_b32 s0, v241, 1
	v_readlane_b32 s1, v241, 2
	s_add_u32 s2, s0, 0xa3a8120
	s_addc_u32 s3, s1, 0
	v_writelane_b32 v238, s2, 34
	s_nop 1
	v_writelane_b32 v238, s3, 35
	s_add_u32 s2, s0, 0xbba8120
	s_addc_u32 s3, s1, 0
	v_writelane_b32 v238, s2, 36
	s_nop 1
	v_writelane_b32 v238, s3, 37
	s_add_u32 s2, s0, 0xcbae100
	v_writelane_b32 v238, s2, 38
	s_addc_u32 s2, s1, 0
	v_writelane_b32 v238, s2, 39
	s_add_u32 s0, s0, 0x10dd4100
	v_writelane_b32 v238, s0, 40
	s_addc_u32 s0, s1, 0
	v_writelane_b32 v238, s0, 41
	s_lshl_b32 s0, s86, 1
	v_writelane_b32 v238, s0, 42
	s_lshl_b32 s0, s89, 1
	v_writelane_b32 v238, s0, 43
	s_add_i32 s0, 0, 0x20000
	v_writelane_b32 v238, s0, 44
	s_add_i32 s0, 0, 0x25800
	v_writelane_b32 v238, s0, 45
	s_add_i32 s0, 0, 0x25804
	v_writelane_b32 v238, s0, 46
	s_add_i32 s0, 0, 0x13000
	v_writelane_b32 v238, s0, 47
	s_add_i32 s0, 0, 0x9400
	v_writelane_b32 v238, s0, 48
	s_add_i32 s0, 0, 0x95f0
	v_writelane_b32 v238, s0, 49
	s_add_i32 s0, 0, 0x962c
	v_writelane_b32 v238, s0, 50
	v_writelane_b32 v238, s94, 51
	s_nop 1
	v_writelane_b32 v238, s95, 52
	v_cmp_gt_i64_e64 s[0:1], s[94:95], v[2:3]
	s_nop 1
	v_writelane_b32 v238, s0, 53
	s_nop 1
	v_writelane_b32 v238, s1, 54
	v_writelane_b32 v238, s96, 55
	s_nop 1
	v_writelane_b32 v238, s97, 56
	v_cmp_gt_i64_e64 s[0:1], s[96:97], v[6:7]
	s_nop 1
	v_writelane_b32 v238, s0, 57
	s_nop 1
	v_writelane_b32 v238, s1, 58
	v_cmp_gt_i64_e64 s[0:1], vcc, v[10:11]
	s_nop 1
	v_writelane_b32 v238, s0, 59
	s_nop 1
	v_writelane_b32 v238, s1, 60
	v_writelane_b32 v238, s84, 61
	s_nop 1
	v_writelane_b32 v238, s85, 62
	v_cmp_gt_i64_e64 s[0:1], s[84:85], v[14:15]
	s_nop 1
	v_writelane_b32 v238, s0, 63
	s_nop 1
	v_writelane_b32 v237, s1, 0
	v_writelane_b32 v237, s80, 1
	s_mov_b64 s[0:1], 0x80
	v_writelane_b32 v237, s89, 2
	v_writelane_b32 v237, s86, 3
	s_branch .LBB0_335
	s_nop 0
	s_nop 0
	s_nop 0
	s_nop 0
	s_nop 0
	s_nop 0
	s_nop 0
	s_nop 0
	s_nop 0
	s_nop 0

; #define PG8_STAGE(bufoff, gbase, voff) do { _Pragma("unroll") for (int _i = 0; _i < 2; ++_i) \
;     __builtin_amdgcn_global_load_lds((const unsigned*)((const char*)(gbase) + (voff)[_i]), (LAS unsigned*)(lds + (bufoff) + ldsw + _i * 8192), 16, 0, 0); } while (0)
; #define PG8_WAIT_V(n) asm volatile("s_waitcnt vmcnt(" #n ")" ::: "memory")
; #define PG8_BAR __builtin_amdgcn_s_barrier()
; template <class Epi, class Sched>
; DI void gemm_phase(LAS unsigned char* lds, const Gemm g, const Sched& S, const Epi& E) {
;     ...
;   const int aoff = lds_byte(wr * 64 + fr, fq * 8), boff = lds_byte(wc * 32 + fr, fq * 8);
;     ...
;   Unit cur, nxt; int ui = 0;
;   if (!S.next(0, cur)) return;
;   f32x4 acc[2][2][4][2];
; #pragma unroll
;   for (int a = 0; a < 2; ++a)
; #pragma unroll
;     for (int b = 0; b < 2; ++b)
; #pragma unroll
;       for (int m = 0; m < 4; ++m)
; #pragma unroll
;         for (int n = 0; n < 2; ++n) acc[a][b][m][n] = (f32x4){0.f, 0.f, 0.f, 0.f};
;   bf16x8 At[4][2], B0[2][2], B1[2][2];
;   const char* cA = (const char*)g.A + (size_t)cur.pm * tstep; const char* cB = (const char*)g.Bt + (size_t)cur.pn * tstep;
;   PG8_STAGE(PG8_SB(0, 0), cB, voffB); PG8_STAGE(PG8_SA(0, 0), cA, voffA); PG8_STAGE(PG8_SB(0, 1), cB + hstep, voffB); PG8_STAGE(PG8_SA(0, 1), cA + hstep, voffA);
;   if (wr == 1) PG8_BAR;
;   PG8_WAIT_V(4); PG8_BAR;
;   PG8_STAGE(PG8_SB(1, 0), cB + kstep, voffB); PG8_STAGE(PG8_SA(1, 0), cA + kstep, voffA); PG8_STAGE(PG8_SB(1, 1), cB + hstep + kstep, voffB);
;   PG8_WAIT_V(6); PG8_BAR;
.LBB0_684:
	s_lshl_b32 s2, s2, 5
	s_and_b32 s61, s2, 0x60
	s_lshl_b32 s60, s3, 6
	s_lshl_b32 s14, s3, 13
	s_lshl_b32 s15, s61, 7
	s_add_u32 s2, s10, 0xa3a8100
	s_addc_u32 s3, s11, 0
	s_add_u32 s4, s10, 0x5f20000
	s_addc_u32 s5, s11, 0
	s_add_u32 s6, s10, 0x5f60000
	s_addc_u32 s7, s11, 0
	s_add_i32 m0, s56, 0x18000
	v_lshl_add_u64 v[6:7], v[6:7], 0, s[0:1]
	s_waitcnt vmcnt(4)
	s_barrier
	global_load_lds_dwordx4 v[6:7], off
	v_lshl_add_u64 v[4:5], v[4:5], 0, s[0:1]
	s_add_i32 m0, s56, 0x1a000
	s_add_i32 s62, s56, 0x8000
	s_add_i32 s63, s56, 0xa000
	global_load_lds_dwordx4 v[4:5], off
	v_lshl_add_u64 v[2:3], v[2:3], 0, s[0:1]
	s_mov_b32 m0, s62
	s_add_u32 s12, s22, 0x40080
	global_load_lds_dwordx4 v[2:3], off
	v_lshl_add_u64 v[0:1], v[0:1], 0, s[0:1]
	s_mov_b32 m0, s63
	s_addc_u32 s13, s23, 0
	global_load_lds_dwordx4 v[0:1], off
	s_add_i32 m0, s56, 0x1c000
	v_lshl_add_u64 v[0:1], s[12:13], 0, v[140:141]
	global_load_lds_dwordx4 v[0:1], off
	v_lshl_add_u64 v[0:1], s[12:13], 0, v[136:137]
	s_add_i32 m0, s56, 0x1e000
	s_movk_i32 s12, 0x3c0
	global_load_lds_dwordx4 v[0:1], off
	v_and_b32_e32 v0, 48, v8
	v_lshlrev_b32_e32 v1, 6, v8
	v_and_or_b32 v0, v1, s12, v0
	v_lshlrev_b32_e32 v1, 2, v8
	v_and_b32_e32 v1, 32, v1
	v_bitop3_b32 v2, v0, s14, v1 bitop3:0xde
	v_bitop3_b32 v196, s15, v0, v1 bitop3:0xf6
	v_lshlrev_b32_e32 v0, 14, v13
	v_and_b32_e32 v0, 0xffff8000, v0
	v_lshl_add_u32 v0, v12, 11, v0
	v_and_b32_e32 v1, 1, v13
	v_lshl_or_b32 v0, v1, 6, v0
	v_lshl_add_u32 v146, v14, 1, v0
	v_lshlrev_b32_e32 v0, 14, v9
	v_and_b32_e32 v0, 0xffff8000, v0
	v_readlane_b32 s12, v240, 32
	s_waitcnt vmcnt(6)
	v_lshl_add_u32 v0, v10, 11, v0
	v_and_b32_e32 v1, 1, v9
	v_readlane_b32 s13, v240, 33
	s_add_u32 s10, s10, 0xcba8100
	v_lshl_or_b32 v0, v1, 6, v0
	s_mov_b32 s35, s12
	v_readlane_b32 s12, v240, 30
	s_addc_u32 s11, s11, 0
	v_mov_b32_e32 v147, v145
	v_lshl_add_u32 v148, v11, 1, v0
	v_mov_b32_e32 v149, v145
	s_mov_b32 s34, 0
	v_add_u32_e32 v197, 0, v2
	s_mov_b32 s36, s12
	s_barrier
	v_readlane_b32 s13, v240, 31
	s_branch .LBB0_686
	s_nop 0
	s_nop 0
	s_nop 0
	s_nop 0
	s_nop 0
	s_nop 0
	s_nop 0
	s_nop 0
	s_nop 0
	s_nop 0

;   DI void operator()(const f32x4 (&acc)[2][2][4][2], const pg8::Unit& u, int wr, int wc, int fr_, int fq_) const {
;     ...
;                 if (gb < 1024) st_bf8((u16*)(big + O_QD) + (size_t)token * 1024 + f8, v, v1, rinv * (0.125f * LOG2E));
;                 else if (gb < 2048) st_bf8((u16*)(big + O_KD) + (size_t)token * 1024 + (f8 - 1024), v, v1, rinv);
;                 else st_bf8((u16*)(big + O_VDT) + (size_t)token * 1024 + (f8 - 2048), v, v1, rinv);
.LBB0_1105:
	s_ashr_i32 s15, s13, 31
	s_add_u32 s20, s13, s61
	s_addc_u32 s21, s15, 0
	v_pk_mul_f32 v[4:5], v[4:5], v[24:25] op_sel_hi:[1,0]
	v_pk_mul_f32 v[6:7], v[6:7], v[24:25] op_sel_hi:[1,0]
	v_pk_mul_f32 v[0:1], v[0:1], v[24:25] op_sel_hi:[1,0]
	v_lshl_add_u64 v[8:9], v[144:145], 0, s[20:21]
	v_cvt_pk_bf16_f32 v4, v4, v5
	v_cvt_pk_bf16_f32 v5, v6, v7
	v_cvt_pk_bf16_f32 v6, v0, v1
	v_pk_mul_f32 v[0:1], v[2:3], v[24:25] op_sel_hi:[1,0]
	v_lshl_add_u64 v[8:9], v[8:9], 1, v[16:17]
	v_cvt_pk_bf16_f32 v7, v0, v1
	global_store_dwordx4 v[8:9], v[4:7], off offset:256
	s_branch .LBB0_685
.Lhop_334:
	s_branch .LBB0_334

; #define PG8_STAGE(bufoff, gbase, voff) do { _Pragma("unroll") for (int _i = 0; _i < 2; ++_i) \
;     __builtin_amdgcn_global_load_lds((const unsigned*)((const char*)(gbase) + (voff)[_i]), (LAS unsigned*)(lds + (bufoff) + ldsw + _i * 8192), 16, 0, 0); } while (0)
; #define PG8_WAIT_V(n) asm volatile("s_waitcnt vmcnt(" #n ")" ::: "memory")
; #define PG8_BAR __builtin_amdgcn_s_barrier()
; template <class Epi, class Sched>
; DI void gemm_phase(LAS unsigned char* lds, const Gemm g, const Sched& S, const Epi& E) {
;     ...
;   const int aoff = lds_byte(wr * 64 + fr, fq * 8), boff = lds_byte(wc * 32 + fr, fq * 8);
;     ...
;   Unit cur, nxt; int ui = 0;
;   if (!S.next(0, cur)) return;
;   f32x4 acc[2][2][4][2];
; #pragma unroll
;   for (int a = 0; a < 2; ++a)
; #pragma unroll
;     for (int b = 0; b < 2; ++b)
; #pragma unroll
;       for (int m = 0; m < 4; ++m)
; #pragma unroll
;         for (int n = 0; n < 2; ++n) acc[a][b][m][n] = (f32x4){0.f, 0.f, 0.f, 0.f};
;   bf16x8 At[4][2], B0[2][2], B1[2][2];
;   const char* cA = (const char*)g.A + (size_t)cur.pm * tstep; const char* cB = (const char*)g.Bt + (size_t)cur.pn * tstep;
;   PG8_STAGE(PG8_SB(0, 0), cB, voffB); PG8_STAGE(PG8_SA(0, 0), cA, voffA); PG8_STAGE(PG8_SB(0, 1), cB + hstep, voffB); PG8_STAGE(PG8_SA(0, 1), cA + hstep, voffA);
;   if (wr == 1) PG8_BAR;
;   PG8_WAIT_V(4); PG8_BAR;
;   PG8_STAGE(PG8_SB(1, 0), cB + kstep, voffB); PG8_STAGE(PG8_SA(1, 0), cA + kstep, voffA); PG8_STAGE(PG8_SB(1, 1), cB + hstep + kstep, voffB);
;   PG8_WAIT_V(6); PG8_BAR;
.LBB0_1192:
	v_and_b32_e32 v17, 48, v16
	v_lshlrev_b32_e32 v18, 6, v16
	s_movk_i32 s4, 0x3c0
	v_lshlrev_b32_e32 v16, 2, v16
	s_lshl_b32 s42, s2, 6
	s_lshl_b32 s2, s2, 13
	v_and_or_b32 v17, v18, s4, v17
	v_and_b32_e32 v16, 32, v16
	v_bitop3_b32 v18, v17, s2, v16 bitop3:0xde
	s_lshl_b32 s2, s3, 5
	s_and_b32 s43, s2, 0x60
	s_lshl_b32 s2, s43, 7
	s_add_u32 s12, s9, 0x5f20000
	s_addc_u32 s13, s24, 0
	s_add_u32 s14, s9, 0x5f60000
	s_addc_u32 s15, s24, 0
	s_add_i32 m0, s38, 0x18000
	v_lshl_add_u64 v[6:7], v[6:7], 0, s[0:1]
	s_waitcnt vmcnt(4)
	s_barrier
	global_load_lds_dwordx4 v[6:7], off
	v_lshl_add_u64 v[4:5], v[4:5], 0, s[0:1]
	s_add_i32 m0, s38, 0x1a000
	s_add_i32 s44, s38, 0x8000
	s_add_i32 s45, s38, 0xa000
	v_bitop3_b32 v162, s2, v17, v16 bitop3:0xf6
	global_load_lds_dwordx4 v[4:5], off
	v_lshl_add_u64 v[2:3], v[2:3], 0, s[0:1]
	s_mov_b32 m0, s44
	s_add_u32 s2, s20, 0x18080
	global_load_lds_dwordx4 v[2:3], off
	v_lshl_add_u64 v[0:1], v[0:1], 0, s[0:1]
	s_mov_b32 m0, s45
	s_addc_u32 s3, s21, 0
	global_load_lds_dwordx4 v[0:1], off
	s_add_i32 m0, s38, 0x1c000
	v_lshl_add_u64 v[0:1], s[2:3], 0, v[130:131]
	global_load_lds_dwordx4 v[0:1], off
	v_lshl_add_u64 v[0:1], s[2:3], 0, v[134:135]
	s_add_i32 m0, s38, 0x1e000
	s_movk_i32 s4, 0x180
	global_load_lds_dwordx4 v[0:1], off
	v_lshrrev_b32_e32 v1, 1, v8
	v_mul_lo_u32 v0, v10, s4
	s_movk_i32 s5, 0x1800
	v_mad_u64_u32 v[0:1], s[2:3], v1, s5, v[0:1]
	v_or_b32_e32 v0, v0, v9
	v_add_lshl_u32 v144, v0, v11, 1
	v_lshrrev_b32_e32 v1, 1, v12
	v_mul_lo_u32 v0, v14, s4
	v_mad_u64_u32 v[0:1], s[2:3], v1, s5, v[0:1]
	s_waitcnt vmcnt(6)
	s_mov_b64 s[22:23], 0x18080
	v_or_b32_e32 v0, v0, v13
	s_add_u32 s16, s9, 0x12da8100
	v_lshl_add_u64 v[136:137], v[144:145], 0, s[22:23]
	v_add_lshl_u32 v144, v0, v15, 1
	s_addc_u32 s17, s24, 0
	v_lshl_add_u64 v[138:139], v[144:145], 0, s[22:23]
	s_mov_b32 s51, 0
	v_add_u32_e32 v163, 0, v18
	s_barrier
	s_branch .LBB0_1195
	s_nop 0
	s_nop 0
	s_nop 0
	s_nop 0
	s_nop 0
	s_nop 0
	s_nop 0
	s_nop 0
	s_nop 0
	s_nop 0
	s_nop 0
	s_nop 0
	s_nop 0
	s_nop 0
	s_nop 0
	s_nop 0
	s_nop 0
	s_nop 0
	s_nop 0
	s_nop 0
	s_nop 0
	s_nop 0
	s_nop 0
	s_nop 0
	s_nop 0
	s_nop 0
	s_nop 0
	s_nop 0
	s_nop 0
	s_nop 0
	s_nop 0
	s_nop 0
	s_nop 0
	s_nop 0
	s_nop 0
	s_nop 0
	s_nop 0
	s_nop 0
	s_nop 0
	s_nop 0
	s_nop 0
	s_nop 0
	s_nop 0
	s_nop 0
	s_nop 0
	s_nop 0
	s_nop 0
	s_nop 0
	s_nop 0
	s_nop 0
	s_nop 0
	s_nop 0
	s_nop 0
	s_nop 0
	s_nop 0
	s_nop 0
	s_nop 0
	s_nop 0
	s_nop 0
	s_nop 0
	s_nop 0
	s_nop 0
	s_nop 0

; #define PG8_STAGE(bufoff, gbase, voff) do { _Pragma("unroll") for (int _i = 0; _i < 2; ++_i) \
;     __builtin_amdgcn_global_load_lds((const unsigned*)((const char*)(gbase) + (voff)[_i]), (LAS unsigned*)(lds + (bufoff) + ldsw + _i * 8192), 16, 0, 0); } while (0)
; #define PG8_WAIT_V(n) asm volatile("s_waitcnt vmcnt(" #n ")" ::: "memory")
; #define PG8_BAR __builtin_amdgcn_s_barrier()
; template <class Epi, class Sched>
; DI void gemm_phase(LAS unsigned char* lds, const Gemm g, const Sched& S, const Epi& E) {
;     ...
;   Unit cur, nxt; int ui = 0;
;   if (!S.next(0, cur)) return;
;   f32x4 acc[2][2][4][2];
; #pragma unroll
;   for (int a = 0; a < 2; ++a)
; #pragma unroll
;     for (int b = 0; b < 2; ++b)
; #pragma unroll
;       for (int m = 0; m < 4; ++m)
; #pragma unroll
;         for (int n = 0; n < 2; ++n) acc[a][b][m][n] = (f32x4){0.f, 0.f, 0.f, 0.f};
;   bf16x8 At[4][2], B0[2][2], B1[2][2];
;   const char* cA = (const char*)g.A + (size_t)cur.pm * tstep; const char* cB = (const char*)g.Bt + (size_t)cur.pn * tstep;
;   PG8_STAGE(PG8_SB(0, 0), cB, voffB); PG8_STAGE(PG8_SA(0, 0), cA, voffA); PG8_STAGE(PG8_SB(0, 1), cB + hstep, voffB); PG8_STAGE(PG8_SA(0, 1), cA + hstep, voffA);
;   if (wr == 1) PG8_BAR;
;   PG8_WAIT_V(4); PG8_BAR;
;   PG8_STAGE(PG8_SB(1, 0), cB + kstep, voffB); PG8_STAGE(PG8_SA(1, 0), cA + kstep, voffA); PG8_STAGE(PG8_SB(1, 1), cB + hstep + kstep, voffB);
;   PG8_WAIT_V(6); PG8_BAR;
;   DI void operator()(const f32x4 (&acc)[2][2][4][2], const pg8::Unit& u, int wr, int wc, int fr_, int fq_) const {
;     ...
;                 if (rsrc) {
.LBB0_1635:
	v_readlane_b32 s48, v241, 13
	v_readlane_b32 s49, v241, 14
	s_lshl_b64 s[6:7], s[6:7], 2
	s_mov_b64 s[16:17], s[48:49]
	s_add_u32 s6, s16, s6
	s_addc_u32 s7, s17, s7
	v_readlane_b32 s10, v237, 11
	s_cmp_eq_u32 s10, 0
	s_cselect_b32 s7, s7, 0
	s_cselect_b32 s6, s6, 0
	s_add_u32 s10, s12, 0x61a4100
	s_addc_u32 s11, s13, 0
	s_add_u32 s12, s12, 0x1a3a8100
	s_addc_u32 s13, s13, 0
	s_and_b32 s46, s15, 3
	v_and_b32_e32 v15, 48, v14
	v_lshlrev_b32_e32 v16, 6, v14
	s_movk_i32 s15, 0x3c0
	v_lshlrev_b32_e32 v14, 2, v14
	v_readlane_b32 s50, v241, 15
	s_lshl_b32 s47, s14, 6
	s_lshl_b32 s14, s14, 13
	v_and_or_b32 v15, v16, s15, v15
	v_and_b32_e32 v14, 32, v14
	s_add_i32 m0, s41, 0x18000
	v_lshl_add_u64 v[6:7], v[6:7], 0, s[0:1]
	v_bitop3_b32 v16, v15, s14, v14 bitop3:0xde
	s_lshl_b32 s48, s46, 5
	s_lshl_b32 s14, s46, 12
	s_waitcnt vmcnt(4)
	s_barrier
	global_load_lds_dwordx4 v[6:7], off
	v_lshl_add_u64 v[4:5], v[4:5], 0, s[0:1]
	s_add_i32 m0, s41, 0x1a000
	s_add_i32 s49, s41, 0x8000
	s_add_i32 s50, s41, 0xa000
	v_bitop3_b32 v158, v15, s14, v14 bitop3:0xde
	global_load_lds_dwordx4 v[4:5], off
	v_lshl_add_u64 v[2:3], v[2:3], 0, s[0:1]
	s_mov_b32 m0, s49
	s_add_u32 s14, s4, 0x40080
	global_load_lds_dwordx4 v[2:3], off
	v_lshl_add_u64 v[0:1], v[0:1], 0, s[0:1]
	s_mov_b32 m0, s50
	s_addc_u32 s15, s5, 0
	global_load_lds_dwordx4 v[0:1], off
	s_add_i32 m0, s41, 0x1c000
	v_lshl_add_u64 v[0:1], s[14:15], 0, v[144:145]
	global_load_lds_dwordx4 v[0:1], off
	v_lshl_add_u64 v[0:1], s[14:15], 0, v[136:137]
	s_add_i32 m0, s41, 0x1e000
	s_cmp_lg_u64 s[6:7], 0
	global_load_lds_dwordx4 v[0:1], off
	v_lshlrev_b32_e32 v0, 14, v12
	v_and_b32_e32 v0, 0xffff8000, v0
	v_lshl_add_u32 v0, v11, 11, v0
	v_and_b32_e32 v1, 1, v12
	v_lshl_or_b32 v0, v1, 6, v0
	v_lshl_add_u32 v142, v13, 1, v0
	v_lshlrev_b32_e32 v0, 14, v8
	v_and_b32_e32 v0, 0xffff8000, v0
	s_waitcnt vmcnt(6)
	v_lshl_add_u32 v0, v9, 11, v0
	v_and_b32_e32 v1, 1, v8
	v_lshl_or_b32 v0, v1, 6, v0
	v_readlane_b32 s16, v240, 53
	s_mov_b32 s45, 0
	s_cselect_b64 s[14:15], -1, 0
	v_mov_b32_e32 v143, v145
	v_lshl_add_u32 v146, v10, 1, v0
	v_mov_b32_e32 v147, v145
	v_add_u32_e32 v159, 0, v16
	v_readlane_b32 s24, v240, 46
	s_mov_b32 s34, s16
	v_readlane_b32 s51, v241, 16
	v_readlane_b32 s52, v241, 17
	v_readlane_b32 s53, v241, 18
	v_readlane_b32 s54, v241, 19
	v_readlane_b32 s55, v241, 20
	v_readlane_b32 s56, v241, 21
	v_readlane_b32 s57, v241, 22
	v_readlane_b32 s58, v241, 23
	v_readlane_b32 s59, v241, 24
	v_readlane_b32 s60, v241, 25
	v_readlane_b32 s61, v241, 26
	v_readlane_b32 s62, v241, 27
	v_readlane_b32 s63, v241, 28
	s_barrier
	v_readlane_b32 s17, v240, 54
	s_branch .LBB0_1637
	s_nop 0
	s_nop 0
	s_nop 0
	s_nop 0
	s_nop 0
	s_nop 0
	s_nop 0
	s_nop 0
	s_nop 0
	s_nop 0
	s_nop 0
	s_nop 0
	s_nop 0
	s_nop 0
	s_nop 0

.LBB0_1781:
	s_cmp_lt_u32 s9, 0x40001
	s_mov_b64 s[22:23], 0
	s_cselect_b64 s[28:29], -1, 0
	s_and_b64 vcc, exec, s[28:29]
	s_cbranch_vccz .LBB0_1775
	s_branch .LBB0_1780
	s_nop 0
	s_nop 0
	s_nop 0
	s_nop 0
	s_nop 0
	s_nop 0
	s_nop 0
	s_nop 0
	s_nop 0
	s_nop 0
